# hyena: conv biases prefetched by scalar loads at unit start; the order loops no longer wait (vmcnt(0)) on the next unit's prefetch loads
# baseline (speedup 1.0000x reference)
.LBB0_624:
	s_or_b64 exec, exec, s[0:1]
	s_load_dwordx4 s[4:7], s[92:93], 0x70
	s_load_dwordx2 s[76:77], s[92:93], 0xb0
	s_mov_b32 s17, s11
	s_lshl_b64 s[2:3], s[16:17], 2
	v_bfe_i32 v23, v22, 28, 1
	v_lshlrev_b32_e32 v15, 3, v22
	s_waitcnt lgkmcnt(0)
	s_lshl_b32 s78, s16, 2
	s_add_u32 s78, s76, s78
	s_addc_u32 s79, s77, 0
	s_load_dword s72, s[78:79], 0x0
	s_load_dword s73, s[78:79], 0x1000
	s_add_u32 s0, s4, s2
	s_addc_u32 s1, s5, s3
	s_load_dword s60, s[0:1], 0x0
	s_load_dword s61, s[0:1], 0x6000
	s_load_dword s62, s[0:1], 0x3000
	s_add_u32 s2, s6, s2
	s_addc_u32 s3, s7, s3
	s_load_dword s63, s[2:3], 0x0
	s_or_b32 s10, s16, 0x400
	s_load_dword s64, s[0:1], 0x4000
	s_load_dword s65, s[0:1], 0x7000
	s_lshl_b64 s[2:3], s[10:11], 2
	s_add_u32 s8, s4, s2
	s_addc_u32 s9, s5, s3
	s_load_dword s66, s[8:9], 0x0
	s_add_u32 s2, s6, s2
	s_addc_u32 s3, s7, s3
	s_load_dword s67, s[2:3], 0x0
	s_or_b32 s10, s16, 0x800
	s_load_dword s68, s[0:1], 0x5000
	s_load_dword s69, s[0:1], 0x8000
	s_lshl_b64 s[0:1], s[10:11], 2
	s_add_u32 s2, s4, s0
	s_addc_u32 s3, s5, s1
	s_add_u32 s0, s6, s0
	s_addc_u32 s1, s7, s1
	s_load_dword s70, s[2:3], 0x0
	s_load_dword s71, s[0:1], 0x0
	v_ashrrev_i32_e32 v16, 31, v22
	v_lshrrev_b32_e32 v23, 22, v23
	v_lshrrev_b32_e32 v26, 25, v16
	v_add_u32_e32 v23, v15, v23
	v_add_u32_e32 v26, v22, v26
	v_and_b32_e32 v23, 0xfffffc00, v23
	s_waitcnt lgkmcnt(0)
	v_mov_b32_e32 v25, s60
	v_mov_b32_e32 v24, s61
	v_mov_b32_e32 v27, s62
	v_mov_b32_e32 v17, s63
	v_mov_b32_e32 v37, s64
	v_mov_b32_e32 v38, s65
	v_mov_b32_e32 v39, s66
	v_mov_b32_e32 v58, s67
	v_mov_b32_e32 v47, s68
	v_mov_b32_e32 v48, s69
	v_mov_b32_e32 v49, s70
	v_mov_b32_e32 v60, s71
	v_and_b32_e32 v30, 0xffff0000, v2
	v_ashrrev_i32_e32 v59, 7, v26
	v_sub_u32_e32 v36, v15, v23
	v_lshlrev_b32_e32 v29, 16, v1
	v_lshlrev_b32_e32 v32, 16, v3
	v_and_b32_e32 v35, 0xffff0000, v5
	v_and_b32_e32 v34, 0xffff0000, v4
	v_lshlrev_b32_e32 v41, 16, v5
	v_lshlrev_b32_e32 v40, 16, v80
	v_mov_b32_e32 v28, v30
	v_lshlrev_b32_e32 v23, 11, v59
	v_lshlrev_b32_e32 v26, 1, v36
	v_lshlrev_b32_e32 v46, 16, v2
	v_and_b32_e32 v31, 0xffff0000, v3
	v_mov_b32_e32 v42, v32
	v_mov_b32_e32 v43, v30
	v_pk_mov_b32 v[44:45], v[40:41], v[34:35] op_sel:[1,0]
	v_add3_u32 v23, 0, v23, v26
	v_lshlrev_b32_e32 v33, 16, v4
	v_cmp_gt_i32_e32 vcc, s30, v22
	v_mov_b32_e32 v50, v25
	v_pk_mul_f32 v[28:29], v[24:25], v[28:29]
	v_mov_b32_e32 v51, v24
	v_mov_b32_e32 v26, v24
	v_pk_mul_f32 v[52:53], v[24:25], v[40:41]
	v_fma_f32 v29, v27, v46, v29
	v_pk_mul_f32 v[54:55], v[50:51], v[30:31]
	v_pk_mul_f32 v[42:43], v[26:27], v[42:43]
	v_mov_b32_e32 v30, v34
	v_pk_mul_f32 v[44:45], v[26:27], v[44:45]
	v_pk_mul_f32 v[56:57], v[50:51], v[32:33]
	v_pk_mul_f32 v[50:51], v[50:51], v[34:35]
	v_fma_f32 v26, v27, v35, v53
	v_add_f32_e32 v34, v28, v29
	v_fma_f32 v35, v25, v46, v43
	v_pk_mul_f32 v[28:29], v[24:25], v[30:31]
	v_fma_f32 v24, v25, v33, v45
	v_fma_f32 v32, v27, v32, v54
	v_fma_f32 v40, v27, v31, v56
	v_fma_f32 v25, v27, v41, v50
	v_add_f32_e32 v31, v42, v35
	v_fma_f32 v27, v27, v33, v29
	v_add_f32_e32 v24, v44, v24
	v_add_f32_e32 v26, v52, v26
	v_add_f32_e32 v30, v17, v34
	v_add_f32_e32 v32, v55, v32
	v_add_f32_e32 v34, v57, v40
	v_add_f32_e32 v25, v51, v25
	v_add_f32_e32 v29, v17, v31
	v_add_f32_e32 v27, v28, v27
	v_add_f32_e32 v28, v17, v24
	v_add_f32_e32 v31, v17, v32
	v_add_f32_e32 v32, v17, v34
	v_add_f32_e32 v33, v17, v25
	v_add_f32_e32 v27, v17, v27
	v_add_f32_e32 v17, v17, v26
	v_cvt_pk_bf16_f32 v24, v30, v29
	v_cvt_pk_bf16_f32 v26, v27, v28
	v_mad_u64_u32 v[28:29], s[0:1], v59, s40, v[36:37]
	v_cvt_pk_bf16_f32 v27, v33, v17
	v_lshl_add_u32 v17, v28, 1, 0
	v_cvt_pk_bf16_f32 v25, v31, v32
	ds_write_b128 v17, v[24:27] offset:128
	v_and_b32_e32 v26, 0xffff0000, v6
	v_lshlrev_b32_e32 v25, 16, v81
	v_mov_b32_e32 v24, v26
	v_lshlrev_b32_e32 v17, 16, v6
	v_pk_mul_f32 v[24:25], v[38:39], v[24:25]
	v_and_b32_e32 v27, 0xffff0000, v7
	v_fma_f32 v25, v37, v17, v25
	v_add_f32_e32 v24, v24, v25
	v_add_f32_e32 v34, v58, v24
	v_mov_b32_e32 v24, v39
	v_mov_b32_e32 v25, v38
	v_pk_mul_f32 v[28:29], v[24:25], v[26:27]
	v_lshlrev_b32_e32 v30, 16, v7
	v_lshlrev_b32_e32 v31, 16, v8
	v_mov_b32_e32 v33, v26
	v_fma_f32 v26, v37, v30, v28
	v_add_f32_e32 v26, v29, v26
	v_pk_mul_f32 v[28:29], v[24:25], v[30:31]
	v_add_f32_e32 v35, v58, v26
	v_fma_f32 v26, v37, v27, v28
	v_add_f32_e32 v26, v29, v26
	v_and_b32_e32 v28, 0xffff0000, v8
	v_mov_b32_e32 v32, v30
	v_add_f32_e32 v30, v58, v26
	v_mov_b32_e32 v26, v28
	v_pk_mul_f32 v[26:27], v[38:39], v[26:27]
	v_mov_b32_e32 v36, v38
	v_fma_f32 v27, v37, v31, v27
	v_pk_mul_f32 v[32:33], v[36:37], v[32:33]
	v_and_b32_e32 v29, 0xffff0000, v9
	v_add_f32_e32 v26, v26, v27
	v_fma_f32 v17, v39, v17, v33
	v_add_f32_e32 v40, v58, v26
	v_pk_mul_f32 v[24:25], v[24:25], v[28:29]
	v_lshlrev_b32_e32 v27, 16, v9
	v_lshlrev_b32_e32 v26, 16, v82
	v_add_f32_e32 v17, v32, v17
	v_pk_mov_b32 v[32:33], v[26:27], v[28:29] op_sel:[1,0]
	v_fma_f32 v24, v37, v27, v24
	v_pk_mul_f32 v[32:33], v[36:37], v[32:33]
	v_add_f32_e32 v24, v25, v24
	v_fma_f32 v28, v39, v31, v33
	v_add_f32_e32 v31, v58, v24
	v_pk_mul_f32 v[24:25], v[38:39], v[26:27]
	v_add_f32_e32 v28, v32, v28
	v_fma_f32 v25, v37, v29, v25
	v_add_f32_e32 v24, v24, v25
	v_add_f32_e32 v28, v58, v28
	v_add_f32_e32 v27, v58, v24
	v_cvt_pk_bf16_f32 v26, v40, v28
	v_add_f32_e32 v17, v58, v17
	v_cvt_pk_bf16_f32 v24, v34, v17
	v_cvt_pk_bf16_f32 v25, v35, v30
	v_cvt_pk_bf16_f32 v27, v31, v27
	ds_write_b128 v23, v[24:27] offset:18560
	v_and_b32_e32 v26, 0xffff0000, v10
	v_lshlrev_b32_e32 v25, 16, v83
	v_mov_b32_e32 v24, v26
	v_lshlrev_b32_e32 v17, 16, v10
	v_pk_mul_f32 v[24:25], v[48:49], v[24:25]
	v_and_b32_e32 v27, 0xffff0000, v11
	v_fma_f32 v25, v47, v17, v25
	v_add_f32_e32 v24, v24, v25
	v_add_f32_e32 v34, v60, v24
	v_mov_b32_e32 v24, v49
	v_mov_b32_e32 v25, v48
	v_pk_mul_f32 v[28:29], v[24:25], v[26:27]
	v_lshlrev_b32_e32 v30, 16, v11
	v_lshlrev_b32_e32 v31, 16, v12
	v_mov_b32_e32 v33, v26
	v_fma_f32 v26, v47, v30, v28
	v_add_f32_e32 v26, v29, v26
	v_pk_mul_f32 v[28:29], v[24:25], v[30:31]
	v_add_f32_e32 v35, v60, v26
	v_fma_f32 v26, v47, v27, v28
	v_add_f32_e32 v26, v29, v26
	v_and_b32_e32 v28, 0xffff0000, v12
	v_mov_b32_e32 v32, v30
	v_add_f32_e32 v30, v60, v26
	v_mov_b32_e32 v26, v28
	v_pk_mul_f32 v[26:27], v[48:49], v[26:27]
	v_mov_b32_e32 v46, v48
	v_fma_f32 v27, v47, v31, v27
	v_pk_mul_f32 v[32:33], v[46:47], v[32:33]
	v_and_b32_e32 v29, 0xffff0000, v13
	v_add_f32_e32 v26, v26, v27
	v_fma_f32 v17, v49, v17, v33
	v_add_f32_e32 v36, v60, v26
	v_pk_mul_f32 v[24:25], v[24:25], v[28:29]
	v_lshlrev_b32_e32 v27, 16, v13
	v_lshlrev_b32_e32 v26, 16, v84
	v_add_f32_e32 v17, v32, v17
	v_pk_mov_b32 v[32:33], v[26:27], v[28:29] op_sel:[1,0]
	v_fma_f32 v24, v47, v27, v24
	v_pk_mul_f32 v[32:33], v[46:47], v[32:33]
	v_add_f32_e32 v24, v25, v24
	v_fma_f32 v28, v49, v31, v33
	v_add_f32_e32 v31, v60, v24
	v_pk_mul_f32 v[24:25], v[48:49], v[26:27]
	v_add_f32_e32 v28, v32, v28
	v_fma_f32 v25, v47, v29, v25
	v_add_f32_e32 v24, v24, v25
	v_add_f32_e32 v27, v60, v24
	v_add_f32_e32 v17, v60, v17
	v_add_f32_e32 v28, v60, v28
	v_cvt_pk_bf16_f32 v24, v34, v17
	v_cvt_pk_bf16_f32 v25, v35, v30
	v_cvt_pk_bf16_f32 v26, v36, v28
	v_cvt_pk_bf16_f32 v27, v31, v27
	ds_write_b128 v23, v[24:27] offset:26752
	s_and_saveexec_b64 s[0:1], vcc
	s_cbranch_execz .LBB0_626
	v_add_u32_sdwa v16, v22, v16 dst_sel:DWORD dst_unused:UNUSED_PAD src0_sel:DWORD src1_sel:BYTE_3
	v_ashrrev_i32_e32 v16, 8, v16
	v_lshlrev_b32_e32 v17, 11, v16
	v_sub_u32_e32 v15, v15, v17
	v_mad_i32_i24 v17, v16, s41, v15
	v_mul_i32_i24_e32 v16, 0x2220, v16
	v_lshlrev_b32_e32 v15, 1, v15
	v_lshl_add_u32 v17, v17, 1, 0
	v_add3_u32 v15, 0, v16, v15
	ds_write_b128 v17, v[18:21] offset:35072
	ds_write_b128 v15, v[18:21] offset:39438

.LBB0_641:
	v_lshl_or_b32 v15, s8, 1, v23
	v_mad_u32_u24 v15, v15, s41, v98
	v_add_u32_e32 v17, 0x8880, v15
	v_add_u32_e32 v40, 0x8800, v15
	s_xor_b64 s[2:3], s[4:5], -1
	ds_read2_b32 v[44:45], v40 offset1:1
	ds_read2_b32 v[40:41], v17 offset1:1
	v_add_u32_e32 v17, 0x8888, v15
	s_and_b64 s[6:7], s[4:5], exec
	ds_read2_b32 v[42:43], v17 offset1:1
	s_cselect_b32 s9, 0, 0x2440
	s_lshl_b32 s6, s8, 10
	s_or_b32 s10, s6, s16
	s_lshl_b64 s[6:7], s[10:11], 2
	s_waitcnt lgkmcnt(0)
	s_add_u32 s6, s0, s6
	s_addc_u32 s7, s1, s7
	s_add_i32 s9, s9, 0
	v_add_u32_e32 v16, s9, v99
	v_add_u32_e32 v48, 0x8840, v15
	v_add_u32_e32 v17, 0x8808, v15
	v_add_u32_e32 v49, 0x8848, v15
	ds_read_b128 v[56:59], v16
	ds_read2_b32 v[46:47], v17 offset1:1
	ds_read2_b32 v[54:55], v49 offset1:1
	ds_read2_b32 v[52:53], v48 offset1:1
	v_add_u32_e32 v17, 0x88c0, v15
	v_add_u32_e32 v50, 0x88c8, v15
	s_waitcnt lgkmcnt(3)
	v_mfma_f32_16x16x32_bf16 v[60:63], v[40:43], v[56:59], 0
	ds_read2_b32 v[48:49], v17 offset1:1
	ds_read2_b32 v[50:51], v50 offset1:1
	ds_read_b128 v[64:67], v16 offset:64
	ds_read_b128 v[108:111], v16 offset:2112
	v_add_u32_e32 v17, 0x8900, v15
	v_add_u32_e32 v116, 0x9008, v15
	s_waitcnt lgkmcnt(6)
	v_mfma_f32_16x16x32_bf16 v[44:47], v[44:47], v[56:59], 0
	v_add_u32_e32 v58, 0x8908, v15
	ds_read2_b32 v[56:57], v17 offset1:1
	ds_read2_b32 v[58:59], v58 offset1:1
	ds_read_b128 v[112:115], v16 offset:128
	v_add_u32_e32 v17, 0x8940, v15
	s_waitcnt lgkmcnt(4)
	v_mfma_f32_16x16x32_bf16 v[60:63], v[48:51], v[64:67], v[60:63]
	v_mfma_f32_16x16x32_bf16 v[44:47], v[52:55], v[64:67], v[44:47]
	v_add_u32_e32 v64, 0x8948, v15
	s_waitcnt lgkmcnt(0)
	v_mfma_f32_16x16x32_bf16 v[52:55], v[56:59], v[112:115], v[60:63]
	s_nop 3
	ds_read2_b32 v[60:61], v17 offset1:1
	ds_read2_b32 v[62:63], v64 offset1:1
	ds_read_b128 v[64:67], v16 offset:192
	v_add_u32_e32 v17, 0x8980, v15
	v_mfma_f32_16x16x32_bf16 v[40:43], v[40:43], v[112:115], v[44:47]
	s_nop 2
	v_add_u32_e32 v46, 0x8988, v15
	ds_read2_b32 v[44:45], v17 offset1:1
	ds_read2_b32 v[46:47], v46 offset1:1
	ds_read_b128 v[112:115], v16 offset:256
	s_waitcnt lgkmcnt(3)
	v_mfma_f32_16x16x32_bf16 v[52:55], v[60:63], v[64:67], v[52:55]
	v_add_u32_e32 v17, 0x89c0, v15
	v_mfma_f32_16x16x32_bf16 v[40:43], v[48:51], v[64:67], v[40:43]
	v_add_u32_e32 v64, 0x89c8, v15
	s_waitcnt lgkmcnt(0)
	v_mfma_f32_16x16x32_bf16 v[48:51], v[44:47], v[112:115], v[52:55]
	s_nop 2
	ds_read2_b32 v[52:53], v17 offset1:1
	ds_read2_b32 v[54:55], v64 offset1:1
	ds_read_b128 v[64:67], v16 offset:320
	v_add_u32_e32 v17, 0x8a00, v15
	v_mfma_f32_16x16x32_bf16 v[40:43], v[56:59], v[112:115], v[40:43]
	v_add_u32_e32 v58, 0x8a08, v15
	ds_read2_b32 v[56:57], v17 offset1:1
	ds_read2_b32 v[58:59], v58 offset1:1
	ds_read_b128 v[112:115], v16 offset:384
	v_add_u32_e32 v17, 0x8a40, v15
	s_waitcnt lgkmcnt(3)
	v_mfma_f32_16x16x32_bf16 v[48:51], v[52:55], v[64:67], v[48:51]
	v_mfma_f32_16x16x32_bf16 v[40:43], v[60:63], v[64:67], v[40:43]
	v_add_u32_e32 v62, 0x8a48, v15
	ds_read2_b32 v[60:61], v17 offset1:1
	ds_read2_b32 v[62:63], v62 offset1:1
	ds_read_b128 v[64:67], v16 offset:448
	v_add_u32_e32 v17, 0x8a80, v15
	s_waitcnt lgkmcnt(3)
	v_mfma_f32_16x16x32_bf16 v[48:51], v[56:59], v[112:115], v[48:51]
	v_mfma_f32_16x16x32_bf16 v[40:43], v[44:47], v[112:115], v[40:43]
	v_add_u32_e32 v46, 0x8a88, v15
	ds_read2_b32 v[44:45], v17 offset1:1
	ds_read2_b32 v[46:47], v46 offset1:1
	ds_read_b128 v[112:115], v16 offset:512
	v_add_u32_e32 v17, 0x8ac0, v15
	s_waitcnt lgkmcnt(3)
	v_mfma_f32_16x16x32_bf16 v[48:51], v[60:63], v[64:67], v[48:51]
	v_mfma_f32_16x16x32_bf16 v[40:43], v[52:55], v[64:67], v[40:43]
	v_add_u32_e32 v54, 0x8ac8, v15
	ds_read2_b32 v[52:53], v17 offset1:1
	ds_read2_b32 v[54:55], v54 offset1:1
	ds_read_b128 v[64:67], v16 offset:576
	v_add_u32_e32 v17, 0x8b00, v15
	s_waitcnt lgkmcnt(3)
	v_mfma_f32_16x16x32_bf16 v[48:51], v[44:47], v[112:115], v[48:51]
	v_mfma_f32_16x16x32_bf16 v[40:43], v[56:59], v[112:115], v[40:43]
	v_add_u32_e32 v58, 0x8b08, v15
	ds_read2_b32 v[56:57], v17 offset1:1
	ds_read2_b32 v[58:59], v58 offset1:1
	ds_read_b128 v[112:115], v16 offset:640
	v_add_u32_e32 v17, 0x8b40, v15
	s_waitcnt lgkmcnt(3)
	v_mfma_f32_16x16x32_bf16 v[48:51], v[52:55], v[64:67], v[48:51]
	v_mfma_f32_16x16x32_bf16 v[40:43], v[60:63], v[64:67], v[40:43]
	v_add_u32_e32 v62, 0x8b48, v15
	ds_read2_b32 v[60:61], v17 offset1:1
	ds_read2_b32 v[62:63], v62 offset1:1
	ds_read_b128 v[64:67], v16 offset:704
	v_add_u32_e32 v17, 0x8b80, v15
	s_waitcnt lgkmcnt(3)
	v_mfma_f32_16x16x32_bf16 v[48:51], v[56:59], v[112:115], v[48:51]
	v_mfma_f32_16x16x32_bf16 v[40:43], v[44:47], v[112:115], v[40:43]
	v_add_u32_e32 v46, 0x8b88, v15
	ds_read2_b32 v[44:45], v17 offset1:1
	ds_read2_b32 v[46:47], v46 offset1:1
	ds_read_b128 v[112:115], v16 offset:768
	v_add_u32_e32 v17, 0x8bc0, v15
	s_waitcnt lgkmcnt(3)
	v_mfma_f32_16x16x32_bf16 v[48:51], v[60:63], v[64:67], v[48:51]
	v_mfma_f32_16x16x32_bf16 v[40:43], v[52:55], v[64:67], v[40:43]
	v_add_u32_e32 v54, 0x8bc8, v15
	ds_read2_b32 v[52:53], v17 offset1:1
	ds_read2_b32 v[54:55], v54 offset1:1
	ds_read_b128 v[64:67], v16 offset:832
	v_add_u32_e32 v17, 0x8c00, v15
	s_waitcnt lgkmcnt(3)
	v_mfma_f32_16x16x32_bf16 v[48:51], v[44:47], v[112:115], v[48:51]
	v_mfma_f32_16x16x32_bf16 v[40:43], v[56:59], v[112:115], v[40:43]
	v_add_u32_e32 v58, 0x8c08, v15
	ds_read2_b32 v[56:57], v17 offset1:1
	ds_read2_b32 v[58:59], v58 offset1:1
	ds_read_b128 v[112:115], v16 offset:896
	v_add_u32_e32 v17, 0x8c40, v15
	s_waitcnt lgkmcnt(3)
	v_mfma_f32_16x16x32_bf16 v[48:51], v[52:55], v[64:67], v[48:51]
	v_mfma_f32_16x16x32_bf16 v[40:43], v[60:63], v[64:67], v[40:43]
	v_add_u32_e32 v62, 0x8c48, v15
	ds_read2_b32 v[60:61], v17 offset1:1
	ds_read2_b32 v[62:63], v62 offset1:1
	ds_read_b128 v[64:67], v16 offset:960
	v_add_u32_e32 v17, 0x8c80, v15
	s_waitcnt lgkmcnt(3)
	v_mfma_f32_16x16x32_bf16 v[48:51], v[56:59], v[112:115], v[48:51]
	v_mfma_f32_16x16x32_bf16 v[40:43], v[44:47], v[112:115], v[40:43]
	v_add_u32_e32 v46, 0x8c88, v15
	ds_read2_b32 v[44:45], v17 offset1:1
	ds_read2_b32 v[46:47], v46 offset1:1
	ds_read_b128 v[112:115], v16 offset:1024
	v_add_u32_e32 v17, 0x8cc0, v15
	s_waitcnt lgkmcnt(3)
	v_mfma_f32_16x16x32_bf16 v[48:51], v[60:63], v[64:67], v[48:51]
	v_mfma_f32_16x16x32_bf16 v[40:43], v[52:55], v[64:67], v[40:43]
	v_add_u32_e32 v54, 0x8cc8, v15
	ds_read2_b32 v[52:53], v17 offset1:1
	ds_read2_b32 v[54:55], v54 offset1:1
	ds_read_b128 v[64:67], v16 offset:1088
	v_add_u32_e32 v17, 0x8d00, v15
	s_waitcnt lgkmcnt(3)
	v_mfma_f32_16x16x32_bf16 v[48:51], v[44:47], v[112:115], v[48:51]
	v_mfma_f32_16x16x32_bf16 v[40:43], v[56:59], v[112:115], v[40:43]
	v_add_u32_e32 v58, 0x8d08, v15
	ds_read2_b32 v[56:57], v17 offset1:1
	ds_read2_b32 v[58:59], v58 offset1:1
	ds_read_b128 v[112:115], v16 offset:1152
	v_add_u32_e32 v17, 0x8d40, v15
	s_waitcnt lgkmcnt(3)
	v_mfma_f32_16x16x32_bf16 v[48:51], v[52:55], v[64:67], v[48:51]
	v_mfma_f32_16x16x32_bf16 v[40:43], v[60:63], v[64:67], v[40:43]
	v_add_u32_e32 v62, 0x8d48, v15
	ds_read2_b32 v[60:61], v17 offset1:1
	ds_read2_b32 v[62:63], v62 offset1:1
	ds_read_b128 v[64:67], v16 offset:1216
	v_add_u32_e32 v17, 0x8d80, v15
	s_waitcnt lgkmcnt(3)
	v_mfma_f32_16x16x32_bf16 v[48:51], v[56:59], v[112:115], v[48:51]
	v_mfma_f32_16x16x32_bf16 v[40:43], v[44:47], v[112:115], v[40:43]
	v_add_u32_e32 v46, 0x8d88, v15
	ds_read2_b32 v[44:45], v17 offset1:1
	ds_read2_b32 v[46:47], v46 offset1:1
	ds_read_b128 v[112:115], v16 offset:1280
	v_add_u32_e32 v17, 0x8dc0, v15
	s_waitcnt lgkmcnt(3)
	v_mfma_f32_16x16x32_bf16 v[48:51], v[60:63], v[64:67], v[48:51]
	v_mfma_f32_16x16x32_bf16 v[40:43], v[52:55], v[64:67], v[40:43]
	v_add_u32_e32 v54, 0x8dc8, v15
	ds_read2_b32 v[52:53], v17 offset1:1
	ds_read2_b32 v[54:55], v54 offset1:1
	ds_read_b128 v[64:67], v16 offset:1344
	v_add_u32_e32 v17, 0x8e00, v15
	s_waitcnt lgkmcnt(3)
	v_mfma_f32_16x16x32_bf16 v[48:51], v[44:47], v[112:115], v[48:51]
	v_mfma_f32_16x16x32_bf16 v[40:43], v[56:59], v[112:115], v[40:43]
	v_add_u32_e32 v58, 0x8e08, v15
	ds_read2_b32 v[56:57], v17 offset1:1
	ds_read2_b32 v[58:59], v58 offset1:1
	ds_read_b128 v[112:115], v16 offset:1408
	v_add_u32_e32 v17, 0x8e40, v15
	s_waitcnt lgkmcnt(3)
	v_mfma_f32_16x16x32_bf16 v[48:51], v[52:55], v[64:67], v[48:51]
	v_mfma_f32_16x16x32_bf16 v[40:43], v[60:63], v[64:67], v[40:43]
	v_add_u32_e32 v62, 0x8e48, v15
	ds_read2_b32 v[60:61], v17 offset1:1
	ds_read2_b32 v[62:63], v62 offset1:1
	ds_read_b128 v[64:67], v16 offset:1472
	v_add_u32_e32 v17, 0x8e80, v15
	s_waitcnt lgkmcnt(3)
	v_mfma_f32_16x16x32_bf16 v[48:51], v[56:59], v[112:115], v[48:51]
	v_mfma_f32_16x16x32_bf16 v[40:43], v[44:47], v[112:115], v[40:43]
	v_add_u32_e32 v46, 0x8e88, v15
	ds_read2_b32 v[44:45], v17 offset1:1
	ds_read2_b32 v[46:47], v46 offset1:1
	ds_read_b128 v[112:115], v16 offset:1536
	v_add_u32_e32 v17, 0x8ec0, v15
	s_waitcnt lgkmcnt(3)
	v_mfma_f32_16x16x32_bf16 v[48:51], v[60:63], v[64:67], v[48:51]
	v_mfma_f32_16x16x32_bf16 v[40:43], v[52:55], v[64:67], v[40:43]
	v_add_u32_e32 v54, 0x8ec8, v15
	ds_read2_b32 v[52:53], v17 offset1:1
	ds_read2_b32 v[54:55], v54 offset1:1
	ds_read_b128 v[64:67], v16 offset:1600
	v_add_u32_e32 v17, 0x8f00, v15
	s_waitcnt lgkmcnt(3)
	v_mfma_f32_16x16x32_bf16 v[48:51], v[44:47], v[112:115], v[48:51]
	v_mfma_f32_16x16x32_bf16 v[40:43], v[56:59], v[112:115], v[40:43]
	v_add_u32_e32 v58, 0x8f08, v15
	ds_read2_b32 v[56:57], v17 offset1:1
	ds_read2_b32 v[58:59], v58 offset1:1
	ds_read_b128 v[112:115], v16 offset:1664
	v_add_u32_e32 v17, 0x8f40, v15
	s_waitcnt lgkmcnt(3)
	v_mfma_f32_16x16x32_bf16 v[48:51], v[52:55], v[64:67], v[48:51]
	v_mfma_f32_16x16x32_bf16 v[40:43], v[60:63], v[64:67], v[40:43]
	v_add_u32_e32 v62, 0x8f48, v15
	ds_read2_b32 v[60:61], v17 offset1:1
	ds_read2_b32 v[62:63], v62 offset1:1
	ds_read_b128 v[64:67], v16 offset:1728
	v_add_u32_e32 v17, 0x8f80, v15
	s_waitcnt lgkmcnt(3)
	v_mfma_f32_16x16x32_bf16 v[48:51], v[56:59], v[112:115], v[48:51]
	v_mfma_f32_16x16x32_bf16 v[40:43], v[44:47], v[112:115], v[40:43]
	v_add_u32_e32 v46, 0x8f88, v15
	ds_read2_b32 v[44:45], v17 offset1:1
	ds_read2_b32 v[46:47], v46 offset1:1
	ds_read_b128 v[112:115], v16 offset:1792
	v_add_u32_e32 v17, 0x8fc0, v15
	s_waitcnt lgkmcnt(3)
	v_mfma_f32_16x16x32_bf16 v[48:51], v[60:63], v[64:67], v[48:51]
	v_mfma_f32_16x16x32_bf16 v[40:43], v[52:55], v[64:67], v[40:43]
	v_add_u32_e32 v54, 0x8fc8, v15
	ds_read2_b32 v[52:53], v17 offset1:1
	ds_read2_b32 v[54:55], v54 offset1:1
	ds_read_b128 v[64:67], v16 offset:1856
	s_waitcnt lgkmcnt(3)
	v_mfma_f32_16x16x32_bf16 v[48:51], v[44:47], v[112:115], v[48:51]
	v_add_u32_e32 v17, 0x9000, v15
	v_mfma_f32_16x16x32_bf16 v[40:43], v[56:59], v[112:115], v[40:43]
	ds_read2_b32 v[56:57], v17 offset1:1
	ds_read2_b32 v[58:59], v116 offset1:1
	ds_read_b128 v[112:115], v16 offset:1920
	v_add_u32_e32 v17, 0x9040, v15
	v_add_u32_e32 v116, 0x9088, v15
	s_waitcnt lgkmcnt(3)
	v_mfma_f32_16x16x32_bf16 v[48:51], v[52:55], v[64:67], v[48:51]
	v_mfma_f32_16x16x32_bf16 v[40:43], v[60:63], v[64:67], v[40:43]
	v_add_u32_e32 v62, 0x9048, v15
	ds_read2_b32 v[60:61], v17 offset1:1
	ds_read2_b32 v[62:63], v62 offset1:1
	v_add_u32_e32 v17, 0x9080, v15
	s_waitcnt lgkmcnt(2)
	v_mfma_f32_16x16x32_bf16 v[48:51], v[56:59], v[112:115], v[48:51]
	ds_read_b128 v[64:67], v16 offset:1984
	v_mfma_f32_16x16x32_bf16 v[40:43], v[44:47], v[112:115], v[40:43]
	ds_read2_b32 v[44:45], v17 offset1:1
	ds_read2_b32 v[46:47], v116 offset1:1
	ds_read_b128 v[112:115], v16 offset:2048
	s_cmp_eq_u32 s8, 0
	s_cselect_b32 s74, s72, s73
	v_mov_b32_e32 v16, s74
	v_add_u32_e32 v17, 0x90c0, v15
	s_waitcnt lgkmcnt(3)
	v_mfma_f32_16x16x32_bf16 v[48:51], v[60:63], v[64:67], v[48:51]
	s_and_b64 s[6:7], s[4:5], exec
	v_add_u32_e32 v15, 0x90c8, v15
	s_cselect_b32 s6, s43, 0x6880
	v_mfma_f32_16x16x32_bf16 v[40:43], v[52:55], v[64:67], v[40:43]
	ds_read2_b32 v[52:53], v17 offset1:1
	ds_read2_b32 v[54:55], v15 offset1:1
	s_add_i32 s10, s6, 0
	v_add_u32_e32 v17, s10, v101
	s_waitcnt lgkmcnt(2)
	v_mfma_f32_16x16x32_bf16 v[44:47], v[44:47], v[112:115], v[48:51]
	v_add_u32_e32 v15, s9, v100
	s_nop 1
	ds_read_b64 v[48:49], v17
	ds_read_b64 v[50:51], v15
	s_and_b64 vcc, exec, s[2:3]
	s_waitcnt lgkmcnt(2)
	v_mfma_f32_16x16x32_bf16 v[44:47], v[52:55], v[108:111], v[44:47]
	s_mov_b64 s[6:7], -1
	s_waitcnt lgkmcnt(1)
	v_lshlrev_b32_e32 v15, 16, v48
	s_waitcnt lgkmcnt(0)
	v_lshlrev_b32_e32 v17, 16, v50
	v_mfma_f32_16x16x32_bf16 v[40:43], v[56:59], v[112:115], v[40:43]
	v_mfma_f32_16x16x32_bf16 v[40:43], v[60:63], v[108:111], v[40:43]
	v_fma_f32 v17, v16, v17, v44
	v_and_b32_e32 v44, 0xffff0000, v50
	v_mul_f32_e32 v15, v17, v15
	v_and_b32_e32 v17, 0xffff0000, v48
	v_fma_f32 v44, v16, v44, v45
	v_lshlrev_b32_e32 v45, 16, v51
	v_mul_f32_e32 v17, v44, v17
	v_lshlrev_b32_e32 v44, 16, v49
	v_fma_f32 v45, v16, v45, v46
	v_and_b32_e32 v46, 0xffff0000, v51
	v_mul_f32_e32 v44, v45, v44
	v_and_b32_e32 v45, 0xffff0000, v49
	v_fmac_f32_e32 v47, v16, v46
	v_mul_f32_e32 v45, v47, v45
	s_cbranch_vccz .LBB0_643
	v_cvt_pk_bf16_f32 v46, v15, v14
	global_store_short v[68:69], v46, off
	v_cvt_pk_bf16_f32 v46, v17, v14
	global_store_short v[68:69], v46, off offset:2048
	v_cvt_pk_bf16_f32 v46, v44, v14
	global_store_short v[70:71], v46, off
	v_cvt_pk_bf16_f32 v46, v45, v14
	global_store_short v[72:73], v46, off
	s_mov_b64 s[6:7], 0

.LBB0_685:
	s_or_b64 exec, exec, s[0:1]
	s_load_dwordx4 s[4:7], s[92:93], 0x70
	s_load_dwordx2 s[76:77], s[92:93], 0xb0
	s_mov_b32 s17, s11
	s_lshl_b64 s[2:3], s[16:17], 2
	v_lshlrev_b32_e32 v15, 3, v22
	v_ashrrev_i32_e32 v16, 31, v22
	s_waitcnt lgkmcnt(0)
	s_lshl_b32 s78, s16, 2
	s_add_u32 s78, s76, s78
	s_addc_u32 s79, s77, 0
	s_load_dword s72, s[78:79], 0x0
	s_load_dword s73, s[78:79], 0x1000
	s_add_u32 s0, s4, s2
	s_addc_u32 s1, s5, s3
	s_load_dword s60, s[0:1], 0x0
	s_load_dword s61, s[0:1], 0x6000
	s_load_dword s62, s[0:1], 0x3000
	s_add_u32 s2, s6, s2
	s_addc_u32 s3, s7, s3
	s_load_dword s63, s[2:3], 0x0
	s_or_b32 s10, s16, 0x400
	s_load_dword s64, s[0:1], 0x4000
	s_load_dword s65, s[0:1], 0x7000
	s_lshl_b64 s[2:3], s[10:11], 2
	s_add_u32 s8, s4, s2
	s_addc_u32 s9, s5, s3
	s_load_dword s66, s[8:9], 0x0
	s_add_u32 s2, s6, s2
	s_addc_u32 s3, s7, s3
	s_load_dword s67, s[2:3], 0x0
	s_or_b32 s10, s16, 0x800
	s_load_dword s68, s[0:1], 0x5000
	s_load_dword s69, s[0:1], 0x8000
	s_lshl_b64 s[0:1], s[10:11], 2
	s_add_u32 s2, s4, s0
	s_addc_u32 s3, s5, s1
	s_add_u32 s0, s6, s0
	s_addc_u32 s1, s7, s1
	s_load_dword s70, s[2:3], 0x0
	s_load_dword s71, s[0:1], 0x0
	v_bfe_i32 v23, v22, 28, 1
	s_waitcnt lgkmcnt(0)
	v_mov_b32_e32 v25, s60
	v_mov_b32_e32 v24, s61
	v_mov_b32_e32 v27, s62
	v_mov_b32_e32 v17, s63
	v_mov_b32_e32 v35, s64
	v_mov_b32_e32 v36, s65
	v_mov_b32_e32 v37, s66
	v_mov_b32_e32 v48, s67
	v_mov_b32_e32 v49, s68
	v_mov_b32_e32 v50, s69
	v_mov_b32_e32 v51, s70
	v_mov_b32_e32 v61, s71
	v_lshrrev_b32_e32 v26, 27, v16
	v_add_u32_sdwa v23, v15, v23 dst_sel:DWORD dst_unused:UNUSED_PAD src0_sel:DWORD src1_sel:BYTE_3
	v_add_u32_e32 v26, v22, v26
	v_and_b32_e32 v23, 0xffffff00, v23
	v_and_b32_e32 v30, 0xffff0000, v2
	v_ashrrev_i32_e32 v60, 5, v26
	v_sub_u32_e32 v34, v15, v23
	v_lshlrev_b32_e32 v29, 16, v1
	v_lshlrev_b32_e32 v32, 16, v3
	v_and_b32_e32 v39, 0xffff0000, v5
	v_and_b32_e32 v38, 0xffff0000, v4
	v_lshlrev_b32_e32 v41, 16, v5
	v_lshlrev_b32_e32 v40, 16, v80
	v_mov_b32_e32 v28, v30
	v_lshlrev_b32_e32 v23, 9, v60
	v_lshlrev_b32_e32 v26, 1, v34
	v_lshlrev_b32_e32 v45, 16, v2
	v_and_b32_e32 v31, 0xffff0000, v3
	v_mov_b32_e32 v42, v32
	v_mov_b32_e32 v43, v30
	v_pk_mov_b32 v[46:47], v[40:41], v[38:39] op_sel:[1,0]
	v_add3_u32 v23, 0, v23, v26
	v_lshlrev_b32_e32 v33, 16, v4
	v_cmp_gt_i32_e32 vcc, s53, v22
	v_mov_b32_e32 v52, v25
	v_pk_mul_f32 v[28:29], v[24:25], v[28:29]
	v_mov_b32_e32 v53, v24
	v_mov_b32_e32 v26, v24
	v_pk_mul_f32 v[54:55], v[24:25], v[40:41]
	v_fma_f32 v29, v27, v45, v29
	v_pk_mul_f32 v[56:57], v[52:53], v[30:31]
	v_pk_mul_f32 v[42:43], v[26:27], v[42:43]
	v_mov_b32_e32 v30, v38
	v_pk_mul_f32 v[46:47], v[26:27], v[46:47]
	v_pk_mul_f32 v[58:59], v[52:53], v[32:33]
	v_pk_mul_f32 v[52:53], v[52:53], v[38:39]
	v_fma_f32 v26, v27, v39, v55
	v_add_f32_e32 v38, v28, v29
	v_fma_f32 v39, v25, v45, v43
	v_pk_mul_f32 v[28:29], v[24:25], v[30:31]
	v_fma_f32 v24, v25, v33, v47
	v_fma_f32 v32, v27, v32, v56
	v_fma_f32 v40, v27, v31, v58
	v_fma_f32 v25, v27, v41, v52
	v_add_f32_e32 v26, v54, v26
	v_add_f32_e32 v31, v42, v39
	v_fma_f32 v27, v27, v33, v29
	v_add_f32_e32 v24, v46, v24
	v_add_f32_e32 v30, v17, v38
	v_add_f32_e32 v32, v57, v32
	v_add_f32_e32 v38, v59, v40
	v_add_f32_e32 v25, v53, v25
	v_add_f32_e32 v29, v17, v26
	v_add_f32_e32 v26, v17, v31
	v_add_f32_e32 v27, v28, v27
	v_add_f32_e32 v28, v17, v24
	v_add_f32_e32 v31, v17, v32
	v_add_f32_e32 v32, v17, v38
	v_add_f32_e32 v33, v17, v25
	v_add_f32_e32 v17, v17, v27
	v_cvt_pk_bf16_f32 v24, v30, v26
	v_cvt_pk_bf16_f32 v26, v17, v28
	v_cvt_pk_bf16_f32 v27, v33, v29
	v_mad_u64_u32 v[28:29], s[0:1], v60, s52, v[34:35]
	v_lshl_add_u32 v17, v28, 1, 0
	v_cvt_pk_bf16_f32 v25, v31, v32
	ds_write_b128 v17, v[24:27] offset:128
	v_and_b32_e32 v26, 0xffff0000, v6
	v_lshlrev_b32_e32 v25, 16, v81
	v_mov_b32_e32 v24, v26
	v_lshlrev_b32_e32 v17, 16, v6
	v_pk_mul_f32 v[24:25], v[36:37], v[24:25]
	v_and_b32_e32 v27, 0xffff0000, v7
	v_fma_f32 v25, v35, v17, v25
	v_add_f32_e32 v24, v24, v25
	v_add_f32_e32 v38, v48, v24
	v_mov_b32_e32 v24, v37
	v_mov_b32_e32 v25, v36
	v_pk_mul_f32 v[28:29], v[24:25], v[26:27]
	v_lshlrev_b32_e32 v30, 16, v7
	v_lshlrev_b32_e32 v31, 16, v8
	v_mov_b32_e32 v33, v26
	v_fma_f32 v26, v35, v30, v28
	v_add_f32_e32 v26, v29, v26
	v_pk_mul_f32 v[28:29], v[24:25], v[30:31]
	v_add_f32_e32 v39, v48, v26
	v_fma_f32 v26, v35, v27, v28
	v_add_f32_e32 v26, v29, v26
	v_and_b32_e32 v28, 0xffff0000, v8
	v_mov_b32_e32 v32, v30
	v_add_f32_e32 v30, v48, v26
	v_mov_b32_e32 v26, v28
	v_pk_mul_f32 v[26:27], v[36:37], v[26:27]
	v_mov_b32_e32 v34, v36
	v_fma_f32 v27, v35, v31, v27
	v_pk_mul_f32 v[32:33], v[34:35], v[32:33]
	v_and_b32_e32 v29, 0xffff0000, v9
	v_add_f32_e32 v26, v26, v27
	v_fma_f32 v17, v37, v17, v33
	v_add_f32_e32 v40, v48, v26
	v_pk_mul_f32 v[24:25], v[24:25], v[28:29]
	v_lshlrev_b32_e32 v27, 16, v9
	v_lshlrev_b32_e32 v26, 16, v82
	v_add_f32_e32 v17, v32, v17
	v_pk_mov_b32 v[32:33], v[26:27], v[28:29] op_sel:[1,0]
	v_fma_f32 v24, v35, v27, v24
	v_pk_mul_f32 v[32:33], v[34:35], v[32:33]
	v_add_f32_e32 v24, v25, v24
	v_fma_f32 v28, v37, v31, v33
	v_add_f32_e32 v31, v48, v24
	v_pk_mul_f32 v[24:25], v[36:37], v[26:27]
	v_add_f32_e32 v28, v32, v28
	v_fma_f32 v25, v35, v29, v25
	v_add_f32_e32 v24, v24, v25
	v_add_f32_e32 v28, v48, v28
	v_add_f32_e32 v27, v48, v24
	v_cvt_pk_bf16_f32 v26, v40, v28
	v_add_f32_e32 v17, v48, v17
	v_cvt_pk_bf16_f32 v24, v38, v17
	v_cvt_pk_bf16_f32 v25, v39, v30
	v_cvt_pk_bf16_f32 v27, v31, v27
	ds_write_b128 v23, v[24:27] offset:25088
	v_and_b32_e32 v26, 0xffff0000, v10
	v_lshlrev_b32_e32 v25, 16, v83
	v_mov_b32_e32 v24, v26
	v_lshlrev_b32_e32 v17, 16, v10
	v_pk_mul_f32 v[24:25], v[50:51], v[24:25]
	v_and_b32_e32 v27, 0xffff0000, v11
	v_fma_f32 v25, v49, v17, v25
	v_add_f32_e32 v24, v24, v25
	v_add_f32_e32 v34, v61, v24
	v_mov_b32_e32 v24, v51
	v_mov_b32_e32 v25, v50
	v_pk_mul_f32 v[28:29], v[24:25], v[26:27]
	v_lshlrev_b32_e32 v30, 16, v11
	v_lshlrev_b32_e32 v31, 16, v12
	v_mov_b32_e32 v33, v26
	v_fma_f32 v26, v49, v30, v28
	v_add_f32_e32 v26, v29, v26
	v_pk_mul_f32 v[28:29], v[24:25], v[30:31]
	v_add_f32_e32 v35, v61, v26
	v_fma_f32 v26, v49, v27, v28
	v_add_f32_e32 v26, v29, v26
	v_and_b32_e32 v28, 0xffff0000, v12
	v_mov_b32_e32 v32, v30
	v_add_f32_e32 v30, v61, v26
	v_mov_b32_e32 v26, v28
	v_pk_mul_f32 v[26:27], v[50:51], v[26:27]
	v_mov_b32_e32 v48, v50
	v_fma_f32 v27, v49, v31, v27
	v_pk_mul_f32 v[32:33], v[48:49], v[32:33]
	v_and_b32_e32 v29, 0xffff0000, v13
	v_add_f32_e32 v26, v26, v27
	v_fma_f32 v17, v51, v17, v33
	v_add_f32_e32 v36, v61, v26
	v_pk_mul_f32 v[24:25], v[24:25], v[28:29]
	v_lshlrev_b32_e32 v27, 16, v13
	v_lshlrev_b32_e32 v26, 16, v84
	v_add_f32_e32 v17, v32, v17
	v_pk_mov_b32 v[32:33], v[26:27], v[28:29] op_sel:[1,0]
	v_fma_f32 v24, v49, v27, v24
	v_pk_mul_f32 v[32:33], v[48:49], v[32:33]
	v_add_f32_e32 v24, v25, v24
	v_fma_f32 v28, v51, v31, v33
	v_add_f32_e32 v31, v61, v24
	v_pk_mul_f32 v[24:25], v[50:51], v[26:27]
	v_add_f32_e32 v28, v32, v28
	v_fma_f32 v25, v49, v29, v25
	v_add_f32_e32 v24, v24, v25
	v_add_f32_e32 v27, v61, v24
	v_add_f32_e32 v17, v61, v17
	v_add_f32_e32 v28, v61, v28
	v_cvt_pk_bf16_f32 v24, v34, v17
	v_cvt_pk_bf16_f32 v25, v35, v30
	v_cvt_pk_bf16_f32 v26, v36, v28
	v_cvt_pk_bf16_f32 v27, v31, v27
	ds_write_b128 v23, v[24:27] offset:33280
	s_and_saveexec_b64 s[0:1], vcc
	s_cbranch_execz .LBB0_687
	v_lshrrev_b32_e32 v16, 26, v16
	v_add_u32_e32 v16, v22, v16
	v_ashrrev_i32_e32 v17, 6, v16
	v_lshlrev_b32_e32 v16, 9, v17
	v_sub_u32_e32 v16, v15, v16
	v_mad_u64_u32 v[24:25], s[2:3], v17, s54, v[16:17]
	v_lshl_add_u32 v15, v24, 1, 0
	ds_write_b128 v15, v[18:21] offset:41600
	v_mul_lo_u32 v15, v17, s55
	v_lshlrev_b32_e32 v16, 1, v16
	v_add3_u32 v15, 0, v15, v16
	ds_write_b128 v15, v[18:21] offset:42894

.LBB0_702:
	s_xor_b64 s[2:3], s[4:5], -1
	s_and_b64 s[6:7], s[4:5], exec
	s_cselect_b32 s9, 0, 0x3100
	s_lshl_b32 s6, s8, 10
	s_or_b32 s10, s6, s16
	s_lshl_b64 s[6:7], s[10:11], 2
	s_waitcnt lgkmcnt(0)
	s_add_u32 s6, s0, s6
	s_addc_u32 s7, s1, s7
	s_cmp_eq_u32 s8, 0
	s_cselect_b32 s74, s72, s73
	v_mov_b32_e32 v15, s74
	v_lshl_or_b32 v17, s8, 1, v23
	s_add_i32 s9, s9, 0
	v_mov_b32_e32 v28, 0
	v_add_u32_e32 v16, s9, v45
	v_mad_u32_u24 v17, v17, s54, v50
	s_mov_b32 s6, -2
	v_mov_b32_e32 v29, v28
	v_mov_b32_e32 v30, v28
	v_mov_b32_e32 v31, v28
	v_mov_b32_e32 v24, v28
	v_mov_b32_e32 v25, v28
	v_mov_b32_e32 v26, v28
	v_mov_b32_e32 v27, v28
.LBB0_703:
	ds_read2_b32 v[52:53], v17 offset0:8 offset1:9
	ds_read2_b32 v[54:55], v17 offset0:10 offset1:11
	ds_read2_b32 v[56:57], v17 offset1:1
	ds_read2_b32 v[58:59], v17 offset0:2 offset1:3
	ds_read_b128 v[60:63], v16
	ds_read2_b32 v[64:65], v17 offset0:24 offset1:25
	ds_read_b128 v[68:71], v16 offset:64
	s_add_i32 s6, s6, 4
	s_cmp_gt_u32 s6, 5
	s_waitcnt lgkmcnt(2)
	v_mfma_f32_16x16x32_bf16 v[28:31], v[52:55], v[60:63], v[28:31]
	ds_read2_b32 v[66:67], v17 offset0:26 offset1:27
	ds_read2_b32 v[52:53], v17 offset0:16 offset1:17
	v_mfma_f32_16x16x32_bf16 v[24:27], v[56:59], v[60:63], v[24:27]
	ds_read2_b32 v[54:55], v17 offset0:18 offset1:19
	ds_read2_b32 v[56:57], v17 offset0:40 offset1:41
	ds_read2_b32 v[58:59], v17 offset0:42 offset1:43
	s_waitcnt lgkmcnt(4)
	v_mfma_f32_16x16x32_bf16 v[28:31], v[64:67], v[68:71], v[28:31]
	s_waitcnt lgkmcnt(2)
	v_mfma_f32_16x16x32_bf16 v[24:27], v[52:55], v[68:71], v[24:27]
	ds_read_b128 v[52:55], v16 offset:128
	ds_read2_b32 v[60:61], v17 offset0:34 offset1:35
	ds_read_b128 v[62:65], v16 offset:192
	v_add_u32_e32 v16, 0x100, v16
	s_waitcnt lgkmcnt(2)
	v_mfma_f32_16x16x32_bf16 v[28:31], v[56:59], v[52:55], v[28:31]
	ds_read2_b32 v[58:59], v17 offset0:32 offset1:33
	ds_read2_b32 v[56:57], v17 offset0:56 offset1:57
	s_waitcnt lgkmcnt(1)
	v_mfma_f32_16x16x32_bf16 v[24:27], v[58:61], v[52:55], v[24:27]
	ds_read2_b32 v[58:59], v17 offset0:58 offset1:59
	ds_read2_b32 v[54:55], v17 offset0:50 offset1:51
	ds_read2_b32 v[52:53], v17 offset0:48 offset1:49
	v_add_u32_e32 v17, 0x100, v17
	s_waitcnt lgkmcnt(2)
	v_mfma_f32_16x16x32_bf16 v[28:31], v[56:59], v[62:65], v[28:31]
	s_waitcnt lgkmcnt(0)
	v_mfma_f32_16x16x32_bf16 v[24:27], v[52:55], v[62:65], v[24:27]
	s_cbranch_scc0 .LBB0_703
	s_and_b64 s[6:7], s[4:5], exec
	s_cselect_b32 s6, s57, 0x8200
	s_add_i32 s10, s6, 0
	v_add_u32_e32 v16, s9, v46
	ds_read_b64 v[52:53], v16
	v_add_u32_e32 v16, s10, v47
	ds_read_b64 v[54:55], v16
	s_mov_b64 s[6:7], -1
	s_and_b64 vcc, exec, s[2:3]
	s_waitcnt lgkmcnt(1)
	v_lshlrev_b32_e32 v16, 16, v52
	v_fma_f32 v16, v15, v16, v28
	s_waitcnt lgkmcnt(0)
	v_lshlrev_b32_e32 v17, 16, v54
	v_and_b32_e32 v28, 0xffff0000, v52
	v_mul_f32_e32 v16, v16, v17
	v_and_b32_e32 v17, 0xffff0000, v54
	v_fma_f32 v28, v15, v28, v29
	v_lshlrev_b32_e32 v29, 16, v53
	v_mul_f32_e32 v17, v28, v17
	v_lshlrev_b32_e32 v28, 16, v55
	v_fma_f32 v29, v15, v29, v30
	v_and_b32_e32 v30, 0xffff0000, v53
	v_mul_f32_e32 v28, v29, v28
	v_and_b32_e32 v29, 0xffff0000, v55
	v_fmac_f32_e32 v31, v15, v30
	v_mul_f32_e32 v29, v31, v29
	s_cbranch_vccz .LBB0_706
	v_cvt_pk_bf16_f32 v30, v16, v14
	global_store_short v[32:33], v30, off
	v_cvt_pk_bf16_f32 v30, v17, v14
	global_store_short v[32:33], v30, off offset:2048
	v_cvt_pk_bf16_f32 v30, v28, v14
	global_store_short v[34:35], v30, off
	v_cvt_pk_bf16_f32 v30, v29, v14
	global_store_short v[36:37], v30, off
	s_mov_b64 s[6:7], 0

.LBB0_1865:
	s_or_b64 exec, exec, s[0:1]
	s_load_dwordx4 s[0:3], s[92:93], 0x70
	s_load_dwordx2 s[76:77], s[92:93], 0xb0
	s_mov_b32 s19, s13
	s_lshl_b64 s[4:5], s[18:19], 2
	v_bfe_i32 v23, v22, 28, 1
	v_lshlrev_b32_e32 v15, 3, v22
	s_waitcnt lgkmcnt(0)
	s_lshl_b32 s78, s18, 2
	s_add_u32 s78, s76, s78
	s_addc_u32 s79, s77, 0
	s_load_dword s72, s[78:79], 0x2000
	s_load_dword s73, s[78:79], 0x3000
	s_add_u32 s0, s0, s4
	s_addc_u32 s1, s1, s5
	s_load_dword s60, s[0:1], 0x9000
	s_load_dword s61, s[0:1], 0xf000
	s_load_dword s62, s[0:1], 0xc000
	s_add_u32 s2, s2, s4
	s_addc_u32 s3, s3, s5
	s_load_dword s63, s[2:3], 0x3000
	s_load_dword s64, s[0:1], 0xa000
	s_load_dword s65, s[0:1], 0xd000
	s_load_dword s66, s[0:1], 0x10000
	s_load_dword s67, s[2:3], 0x4000
	v_ashrrev_i32_e32 v16, 31, v22
	v_lshrrev_b32_e32 v23, 22, v23
	v_lshrrev_b32_e32 v26, 25, v16
	v_add_u32_e32 v23, v15, v23
	v_add_u32_e32 v26, v22, v26
	v_and_b32_e32 v23, 0xfffffc00, v23
	v_ashrrev_i32_e32 v50, 7, v26
	v_sub_u32_e32 v26, v15, v23
	v_lshlrev_b32_e32 v23, 11, v50
	v_lshlrev_b32_e32 v53, 1, v26
	v_add3_u32 v23, 0, v23, v53
	s_waitcnt lgkmcnt(0)
	v_mov_b32_e32 v25, s60
	v_mov_b32_e32 v24, s61
	v_mov_b32_e32 v27, s62
	v_mov_b32_e32 v17, s63
	v_mov_b32_e32 v29, s64
	v_mov_b32_e32 v31, s65
	v_mov_b32_e32 v28, s66
	v_mov_b32_e32 v52, s67
	v_and_b32_e32 v34, 0xffff0000, v2
	v_lshlrev_b32_e32 v33, 16, v1
	v_lshlrev_b32_e32 v36, 16, v3
	v_and_b32_e32 v39, 0xffff0000, v5
	v_and_b32_e32 v38, 0xffff0000, v4
	v_lshlrev_b32_e32 v41, 16, v5
	v_lshlrev_b32_e32 v40, 16, v80
	v_mov_b32_e32 v32, v34
	v_lshlrev_b32_e32 v30, 16, v2
	v_and_b32_e32 v35, 0xffff0000, v3
	v_lshlrev_b32_e32 v37, 16, v4
	v_mov_b32_e32 v46, v36
	v_mov_b32_e32 v47, v34
	v_pk_mov_b32 v[48:49], v[40:41], v[38:39] op_sel:[1,0]
	v_and_b32_e32 v44, 0xffff0000, v6
	v_lshlrev_b32_e32 v43, 16, v81
	v_mov_b32_e32 v42, v44
	v_lshlrev_b32_e32 v62, 16, v6
	v_and_b32_e32 v45, 0xffff0000, v7
	v_cmp_gt_i32_e32 vcc, s34, v22
	v_mov_b32_e32 v54, v25
	v_pk_mul_f32 v[32:33], v[24:25], v[32:33]
	v_mad_u64_u32 v[50:51], s[4:5], v50, s42, v[26:27]
	v_lshl_add_u32 v63, v50, 1, 0
	s_load_dword s68, s[0:1], 0xb000
	s_load_dword s69, s[0:1], 0xe000
	s_load_dword s70, s[0:1], 0x11000
	s_load_dword s71, s[2:3], 0x5000
	v_mov_b32_e32 v55, v24
	v_mov_b32_e32 v26, v24
	v_pk_mul_f32 v[56:57], v[24:25], v[40:41]
	v_fma_f32 v33, v27, v30, v33
	v_pk_mul_f32 v[58:59], v[54:55], v[34:35]
	v_pk_mul_f32 v[46:47], v[26:27], v[46:47]
	v_pk_mul_f32 v[60:61], v[54:55], v[36:37]
	v_mov_b32_e32 v34, v38
	v_pk_mul_f32 v[54:55], v[54:55], v[38:39]
	v_pk_mul_f32 v[48:49], v[26:27], v[48:49]
	v_fma_f32 v26, v27, v39, v57
	v_add_f32_e32 v38, v32, v33
	v_fma_f32 v30, v25, v30, v47
	v_fma_f32 v36, v27, v36, v58
	v_fma_f32 v39, v27, v35, v60
	v_pk_mul_f32 v[32:33], v[24:25], v[34:35]
	v_fma_f32 v24, v25, v37, v49
	v_fma_f32 v25, v27, v41, v54
	v_add_f32_e32 v26, v56, v26
	v_add_f32_e32 v30, v46, v30
	v_add_f32_e32 v35, v59, v36
	v_add_f32_e32 v36, v61, v39
	v_fma_f32 v27, v27, v37, v33
	v_add_f32_e32 v24, v48, v24
	v_add_f32_e32 v25, v55, v25
	s_waitcnt lgkmcnt(0)
	v_mov_b32_e32 v51, s68
	v_mov_b32_e32 v53, s69
	v_mov_b32_e32 v50, s70
	v_mov_b32_e32 v64, s71
	v_add_f32_e32 v34, v17, v38
	v_add_f32_e32 v26, v17, v26
	v_add_f32_e32 v30, v17, v30
	v_add_f32_e32 v33, v17, v35
	v_add_f32_e32 v35, v17, v36
	v_add_f32_e32 v27, v32, v27
	v_add_f32_e32 v32, v17, v24
	v_add_f32_e32 v36, v17, v25
	v_cvt_pk_bf16_f32 v24, v34, v30
	v_cvt_pk_bf16_f32 v25, v33, v35
	v_add_f32_e32 v17, v17, v27
	v_cvt_pk_bf16_f32 v27, v36, v26
	v_cvt_pk_bf16_f32 v26, v17, v32
	ds_write_b128 v63, v[24:27] offset:128
	v_pk_mul_f32 v[24:25], v[28:29], v[42:43]
	v_lshlrev_b32_e32 v32, 16, v7
	v_fma_f32 v17, v31, v62, v25
	v_add_f32_e32 v17, v24, v17
	v_mov_b32_e32 v24, v29
	v_mov_b32_e32 v25, v28
	v_pk_mul_f32 v[26:27], v[24:25], v[44:45]
	v_lshlrev_b32_e32 v33, 16, v8
	v_fma_f32 v26, v31, v32, v26
	v_add_f32_e32 v26, v27, v26
	v_add_f32_e32 v39, v52, v26
	v_pk_mul_f32 v[26:27], v[24:25], v[32:33]
	v_mov_b32_e32 v30, v28
	v_mov_b32_e32 v34, v32
	v_mov_b32_e32 v35, v44
	v_fma_f32 v26, v31, v45, v26
	v_pk_mul_f32 v[34:35], v[30:31], v[34:35]
	v_add_f32_e32 v26, v27, v26
	v_fma_f32 v35, v29, v62, v35
	v_add_f32_e32 v32, v52, v26
	v_and_b32_e32 v26, 0xffff0000, v8
	v_add_f32_e32 v34, v34, v35
	v_mov_b32_e32 v44, v26
	v_add_f32_e32 v38, v52, v34
	v_pk_mul_f32 v[34:35], v[28:29], v[44:45]
	v_and_b32_e32 v27, 0xffff0000, v9
	v_fma_f32 v35, v31, v33, v35
	v_add_f32_e32 v34, v34, v35
	v_add_f32_e32 v40, v52, v34
	v_pk_mul_f32 v[24:25], v[24:25], v[26:27]
	v_lshlrev_b32_e32 v35, 16, v9
	v_lshlrev_b32_e32 v34, 16, v82
	v_pk_mov_b32 v[36:37], v[34:35], v[26:27] op_sel:[1,0]
	v_fma_f32 v24, v31, v35, v24
	v_pk_mul_f32 v[36:37], v[30:31], v[36:37]
	v_add_f32_e32 v24, v25, v24
	v_fma_f32 v26, v29, v33, v37
	v_add_f32_e32 v30, v52, v24
	v_pk_mul_f32 v[24:25], v[28:29], v[34:35]
	v_add_f32_e32 v26, v36, v26
	v_fma_f32 v25, v31, v27, v25
	v_add_f32_e32 v26, v52, v26
	v_add_f32_e32 v24, v24, v25
	v_add_f32_e32 v27, v52, v24
	v_cvt_pk_bf16_f32 v26, v40, v26
	v_add_f32_e32 v17, v52, v17
	v_cvt_pk_bf16_f32 v24, v17, v38
	v_cvt_pk_bf16_f32 v25, v39, v32
	v_cvt_pk_bf16_f32 v27, v30, v27
	ds_write_b128 v23, v[24:27] offset:18560
	v_and_b32_e32 v26, 0xffff0000, v10
	v_lshlrev_b32_e32 v25, 16, v83
	v_mov_b32_e32 v24, v26
	v_lshlrev_b32_e32 v17, 16, v10
	v_pk_mul_f32 v[24:25], v[50:51], v[24:25]
	v_and_b32_e32 v27, 0xffff0000, v11
	v_fma_f32 v25, v53, v17, v25
	v_add_f32_e32 v24, v24, v25
	v_add_f32_e32 v34, v64, v24
	v_mov_b32_e32 v24, v51
	v_mov_b32_e32 v25, v50
	v_pk_mul_f32 v[28:29], v[24:25], v[26:27]
	v_lshlrev_b32_e32 v30, 16, v11
	v_lshlrev_b32_e32 v31, 16, v12
	v_mov_b32_e32 v33, v26
	v_fma_f32 v26, v53, v30, v28
	v_add_f32_e32 v26, v29, v26
	v_pk_mul_f32 v[28:29], v[24:25], v[30:31]
	v_add_f32_e32 v35, v64, v26
	v_fma_f32 v26, v53, v27, v28
	v_add_f32_e32 v26, v29, v26
	v_and_b32_e32 v28, 0xffff0000, v12
	v_mov_b32_e32 v32, v30
	v_add_f32_e32 v30, v64, v26
	v_mov_b32_e32 v26, v28
	v_pk_mul_f32 v[26:27], v[50:51], v[26:27]
	v_mov_b32_e32 v52, v50
	v_fma_f32 v27, v53, v31, v27
	v_pk_mul_f32 v[32:33], v[52:53], v[32:33]
	v_and_b32_e32 v29, 0xffff0000, v13
	v_add_f32_e32 v26, v26, v27
	v_fma_f32 v17, v51, v17, v33
	v_add_f32_e32 v36, v64, v26
	v_pk_mul_f32 v[24:25], v[24:25], v[28:29]
	v_lshlrev_b32_e32 v27, 16, v13
	v_lshlrev_b32_e32 v26, 16, v84
	v_add_f32_e32 v17, v32, v17
	v_pk_mov_b32 v[32:33], v[26:27], v[28:29] op_sel:[1,0]
	v_fma_f32 v24, v53, v27, v24
	v_pk_mul_f32 v[32:33], v[52:53], v[32:33]
	v_add_f32_e32 v24, v25, v24
	v_fma_f32 v28, v51, v31, v33
	v_add_f32_e32 v31, v64, v24
	v_pk_mul_f32 v[24:25], v[50:51], v[26:27]
	v_add_f32_e32 v28, v32, v28
	v_fma_f32 v25, v53, v29, v25
	v_add_f32_e32 v24, v24, v25
	v_add_f32_e32 v27, v64, v24
	v_add_f32_e32 v17, v64, v17
	v_add_f32_e32 v28, v64, v28
	v_cvt_pk_bf16_f32 v24, v34, v17
	v_cvt_pk_bf16_f32 v25, v35, v30
	v_cvt_pk_bf16_f32 v26, v36, v28
	v_cvt_pk_bf16_f32 v27, v31, v27
	ds_write_b128 v23, v[24:27] offset:26752
	s_and_saveexec_b64 s[0:1], vcc
	s_cbranch_execz .LBB0_1867
	v_add_u32_sdwa v16, v22, v16 dst_sel:DWORD dst_unused:UNUSED_PAD src0_sel:DWORD src1_sel:BYTE_3
	v_ashrrev_i32_e32 v16, 8, v16
	v_lshlrev_b32_e32 v17, 11, v16
	v_sub_u32_e32 v15, v15, v17
	v_mad_i32_i24 v17, v16, s43, v15
	v_mul_i32_i24_e32 v16, 0x2220, v16
	v_lshlrev_b32_e32 v15, 1, v15
	v_lshl_add_u32 v17, v17, 1, 0
	v_add3_u32 v15, 0, v16, v15
	ds_write_b128 v17, v[18:21] offset:35072
	ds_write_b128 v15, v[18:21] offset:39438

.LBB0_1882:
	v_lshl_or_b32 v15, s8, 1, v23
	v_mad_u32_u24 v15, v15, s43, v105
	v_add_u32_e32 v17, 0x8880, v15
	v_add_u32_e32 v40, 0x8800, v15
	s_xor_b64 s[2:3], s[4:5], -1
	ds_read2_b32 v[44:45], v40 offset1:1
	ds_read2_b32 v[40:41], v17 offset1:1
	v_add_u32_e32 v17, 0x8888, v15
	s_and_b64 s[6:7], s[4:5], exec
	ds_read2_b32 v[42:43], v17 offset1:1
	s_cselect_b32 s9, 0, 0x2440
	s_lshl_b32 s6, s8, 10
	s_or_b32 s12, s6, s18
	s_lshl_b64 s[6:7], s[12:13], 2
	s_waitcnt lgkmcnt(0)
	s_add_u32 s6, s0, s6
	s_addc_u32 s7, s1, s7
	s_add_i32 s9, s9, 0
	v_add_u32_e32 v16, s9, v106
	v_add_u32_e32 v48, 0x8840, v15
	v_add_u32_e32 v17, 0x8808, v15
	v_add_u32_e32 v49, 0x8848, v15
	ds_read_b128 v[56:59], v16
	ds_read2_b32 v[46:47], v17 offset1:1
	ds_read2_b32 v[54:55], v49 offset1:1
	ds_read2_b32 v[52:53], v48 offset1:1
	v_add_u32_e32 v17, 0x88c0, v15
	v_add_u32_e32 v50, 0x88c8, v15
	s_waitcnt lgkmcnt(3)
	v_mfma_f32_16x16x32_bf16 v[60:63], v[40:43], v[56:59], 0
	ds_read2_b32 v[48:49], v17 offset1:1
	ds_read2_b32 v[50:51], v50 offset1:1
	ds_read_b128 v[64:67], v16 offset:64
	ds_read_b128 v[116:119], v16 offset:2112
	v_add_u32_e32 v17, 0x8900, v15
	v_add_u32_e32 v115, 0x9008, v15
	s_waitcnt lgkmcnt(6)
	v_mfma_f32_16x16x32_bf16 v[44:47], v[44:47], v[56:59], 0
	v_add_u32_e32 v58, 0x8908, v15
	ds_read2_b32 v[56:57], v17 offset1:1
	ds_read2_b32 v[58:59], v58 offset1:1
	ds_read_b128 v[120:123], v16 offset:128
	v_add_u32_e32 v17, 0x8940, v15
	s_waitcnt lgkmcnt(4)
	v_mfma_f32_16x16x32_bf16 v[60:63], v[48:51], v[64:67], v[60:63]
	v_mfma_f32_16x16x32_bf16 v[44:47], v[52:55], v[64:67], v[44:47]
	v_add_u32_e32 v64, 0x8948, v15
	s_waitcnt lgkmcnt(0)
	v_mfma_f32_16x16x32_bf16 v[52:55], v[56:59], v[120:123], v[60:63]
	s_nop 3
	ds_read2_b32 v[60:61], v17 offset1:1
	ds_read2_b32 v[62:63], v64 offset1:1
	ds_read_b128 v[64:67], v16 offset:192
	v_add_u32_e32 v17, 0x8980, v15
	v_mfma_f32_16x16x32_bf16 v[40:43], v[40:43], v[120:123], v[44:47]
	s_nop 2
	v_add_u32_e32 v46, 0x8988, v15
	ds_read2_b32 v[44:45], v17 offset1:1
	ds_read2_b32 v[46:47], v46 offset1:1
	ds_read_b128 v[120:123], v16 offset:256
	s_waitcnt lgkmcnt(3)
	v_mfma_f32_16x16x32_bf16 v[52:55], v[60:63], v[64:67], v[52:55]
	v_add_u32_e32 v17, 0x89c0, v15
	v_mfma_f32_16x16x32_bf16 v[40:43], v[48:51], v[64:67], v[40:43]
	v_add_u32_e32 v64, 0x89c8, v15
	s_waitcnt lgkmcnt(0)
	v_mfma_f32_16x16x32_bf16 v[48:51], v[44:47], v[120:123], v[52:55]
	s_nop 2
	ds_read2_b32 v[52:53], v17 offset1:1
	ds_read2_b32 v[54:55], v64 offset1:1
	ds_read_b128 v[64:67], v16 offset:320
	v_add_u32_e32 v17, 0x8a00, v15
	v_mfma_f32_16x16x32_bf16 v[40:43], v[56:59], v[120:123], v[40:43]
	v_add_u32_e32 v58, 0x8a08, v15
	ds_read2_b32 v[56:57], v17 offset1:1
	ds_read2_b32 v[58:59], v58 offset1:1
	ds_read_b128 v[120:123], v16 offset:384
	v_add_u32_e32 v17, 0x8a40, v15
	s_waitcnt lgkmcnt(3)
	v_mfma_f32_16x16x32_bf16 v[48:51], v[52:55], v[64:67], v[48:51]
	v_mfma_f32_16x16x32_bf16 v[40:43], v[60:63], v[64:67], v[40:43]
	v_add_u32_e32 v62, 0x8a48, v15
	ds_read2_b32 v[60:61], v17 offset1:1
	ds_read2_b32 v[62:63], v62 offset1:1
	ds_read_b128 v[64:67], v16 offset:448
	v_add_u32_e32 v17, 0x8a80, v15
	s_waitcnt lgkmcnt(3)
	v_mfma_f32_16x16x32_bf16 v[48:51], v[56:59], v[120:123], v[48:51]
	v_mfma_f32_16x16x32_bf16 v[40:43], v[44:47], v[120:123], v[40:43]
	v_add_u32_e32 v46, 0x8a88, v15
	ds_read2_b32 v[44:45], v17 offset1:1
	ds_read2_b32 v[46:47], v46 offset1:1
	ds_read_b128 v[120:123], v16 offset:512
	v_add_u32_e32 v17, 0x8ac0, v15
	s_waitcnt lgkmcnt(3)
	v_mfma_f32_16x16x32_bf16 v[48:51], v[60:63], v[64:67], v[48:51]
	v_mfma_f32_16x16x32_bf16 v[40:43], v[52:55], v[64:67], v[40:43]
	v_add_u32_e32 v54, 0x8ac8, v15
	ds_read2_b32 v[52:53], v17 offset1:1
	ds_read2_b32 v[54:55], v54 offset1:1
	ds_read_b128 v[64:67], v16 offset:576
	v_add_u32_e32 v17, 0x8b00, v15
	s_waitcnt lgkmcnt(3)
	v_mfma_f32_16x16x32_bf16 v[48:51], v[44:47], v[120:123], v[48:51]
	v_mfma_f32_16x16x32_bf16 v[40:43], v[56:59], v[120:123], v[40:43]
	v_add_u32_e32 v58, 0x8b08, v15
	ds_read2_b32 v[56:57], v17 offset1:1
	ds_read2_b32 v[58:59], v58 offset1:1
	ds_read_b128 v[120:123], v16 offset:640
	v_add_u32_e32 v17, 0x8b40, v15
	s_waitcnt lgkmcnt(3)
	v_mfma_f32_16x16x32_bf16 v[48:51], v[52:55], v[64:67], v[48:51]
	v_mfma_f32_16x16x32_bf16 v[40:43], v[60:63], v[64:67], v[40:43]
	v_add_u32_e32 v62, 0x8b48, v15
	ds_read2_b32 v[60:61], v17 offset1:1
	ds_read2_b32 v[62:63], v62 offset1:1
	ds_read_b128 v[64:67], v16 offset:704
	v_add_u32_e32 v17, 0x8b80, v15
	s_waitcnt lgkmcnt(3)
	v_mfma_f32_16x16x32_bf16 v[48:51], v[56:59], v[120:123], v[48:51]
	v_mfma_f32_16x16x32_bf16 v[40:43], v[44:47], v[120:123], v[40:43]
	v_add_u32_e32 v46, 0x8b88, v15
	ds_read2_b32 v[44:45], v17 offset1:1
	ds_read2_b32 v[46:47], v46 offset1:1
	ds_read_b128 v[120:123], v16 offset:768
	v_add_u32_e32 v17, 0x8bc0, v15
	s_waitcnt lgkmcnt(3)
	v_mfma_f32_16x16x32_bf16 v[48:51], v[60:63], v[64:67], v[48:51]
	v_mfma_f32_16x16x32_bf16 v[40:43], v[52:55], v[64:67], v[40:43]
	v_add_u32_e32 v54, 0x8bc8, v15
	ds_read2_b32 v[52:53], v17 offset1:1
	ds_read2_b32 v[54:55], v54 offset1:1
	ds_read_b128 v[64:67], v16 offset:832
	v_add_u32_e32 v17, 0x8c00, v15
	s_waitcnt lgkmcnt(3)
	v_mfma_f32_16x16x32_bf16 v[48:51], v[44:47], v[120:123], v[48:51]
	v_mfma_f32_16x16x32_bf16 v[40:43], v[56:59], v[120:123], v[40:43]
	v_add_u32_e32 v58, 0x8c08, v15
	ds_read2_b32 v[56:57], v17 offset1:1
	ds_read2_b32 v[58:59], v58 offset1:1
	ds_read_b128 v[120:123], v16 offset:896
	v_add_u32_e32 v17, 0x8c40, v15
	s_waitcnt lgkmcnt(3)
	v_mfma_f32_16x16x32_bf16 v[48:51], v[52:55], v[64:67], v[48:51]
	v_mfma_f32_16x16x32_bf16 v[40:43], v[60:63], v[64:67], v[40:43]
	v_add_u32_e32 v62, 0x8c48, v15
	ds_read2_b32 v[60:61], v17 offset1:1
	ds_read2_b32 v[62:63], v62 offset1:1
	ds_read_b128 v[64:67], v16 offset:960
	v_add_u32_e32 v17, 0x8c80, v15
	s_waitcnt lgkmcnt(3)
	v_mfma_f32_16x16x32_bf16 v[48:51], v[56:59], v[120:123], v[48:51]
	v_mfma_f32_16x16x32_bf16 v[40:43], v[44:47], v[120:123], v[40:43]
	v_add_u32_e32 v46, 0x8c88, v15
	ds_read2_b32 v[44:45], v17 offset1:1
	ds_read2_b32 v[46:47], v46 offset1:1
	ds_read_b128 v[120:123], v16 offset:1024
	v_add_u32_e32 v17, 0x8cc0, v15
	s_waitcnt lgkmcnt(3)
	v_mfma_f32_16x16x32_bf16 v[48:51], v[60:63], v[64:67], v[48:51]
	v_mfma_f32_16x16x32_bf16 v[40:43], v[52:55], v[64:67], v[40:43]
	v_add_u32_e32 v54, 0x8cc8, v15
	ds_read2_b32 v[52:53], v17 offset1:1
	ds_read2_b32 v[54:55], v54 offset1:1
	ds_read_b128 v[64:67], v16 offset:1088
	v_add_u32_e32 v17, 0x8d00, v15
	s_waitcnt lgkmcnt(3)
	v_mfma_f32_16x16x32_bf16 v[48:51], v[44:47], v[120:123], v[48:51]
	v_mfma_f32_16x16x32_bf16 v[40:43], v[56:59], v[120:123], v[40:43]
	v_add_u32_e32 v58, 0x8d08, v15
	ds_read2_b32 v[56:57], v17 offset1:1
	ds_read2_b32 v[58:59], v58 offset1:1
	ds_read_b128 v[120:123], v16 offset:1152
	v_add_u32_e32 v17, 0x8d40, v15
	s_waitcnt lgkmcnt(3)
	v_mfma_f32_16x16x32_bf16 v[48:51], v[52:55], v[64:67], v[48:51]
	v_mfma_f32_16x16x32_bf16 v[40:43], v[60:63], v[64:67], v[40:43]
	v_add_u32_e32 v62, 0x8d48, v15
	ds_read2_b32 v[60:61], v17 offset1:1
	ds_read2_b32 v[62:63], v62 offset1:1
	ds_read_b128 v[64:67], v16 offset:1216
	v_add_u32_e32 v17, 0x8d80, v15
	s_waitcnt lgkmcnt(3)
	v_mfma_f32_16x16x32_bf16 v[48:51], v[56:59], v[120:123], v[48:51]
	v_mfma_f32_16x16x32_bf16 v[40:43], v[44:47], v[120:123], v[40:43]
	v_add_u32_e32 v46, 0x8d88, v15
	ds_read2_b32 v[44:45], v17 offset1:1
	ds_read2_b32 v[46:47], v46 offset1:1
	ds_read_b128 v[120:123], v16 offset:1280
	v_add_u32_e32 v17, 0x8dc0, v15
	s_waitcnt lgkmcnt(3)
	v_mfma_f32_16x16x32_bf16 v[48:51], v[60:63], v[64:67], v[48:51]
	v_mfma_f32_16x16x32_bf16 v[40:43], v[52:55], v[64:67], v[40:43]
	v_add_u32_e32 v54, 0x8dc8, v15
	ds_read2_b32 v[52:53], v17 offset1:1
	ds_read2_b32 v[54:55], v54 offset1:1
	ds_read_b128 v[64:67], v16 offset:1344
	v_add_u32_e32 v17, 0x8e00, v15
	s_waitcnt lgkmcnt(3)
	v_mfma_f32_16x16x32_bf16 v[48:51], v[44:47], v[120:123], v[48:51]
	v_mfma_f32_16x16x32_bf16 v[40:43], v[56:59], v[120:123], v[40:43]
	v_add_u32_e32 v58, 0x8e08, v15
	ds_read2_b32 v[56:57], v17 offset1:1
	ds_read2_b32 v[58:59], v58 offset1:1
	ds_read_b128 v[120:123], v16 offset:1408
	v_add_u32_e32 v17, 0x8e40, v15
	s_waitcnt lgkmcnt(3)
	v_mfma_f32_16x16x32_bf16 v[48:51], v[52:55], v[64:67], v[48:51]
	v_mfma_f32_16x16x32_bf16 v[40:43], v[60:63], v[64:67], v[40:43]
	v_add_u32_e32 v62, 0x8e48, v15
	ds_read2_b32 v[60:61], v17 offset1:1
	ds_read2_b32 v[62:63], v62 offset1:1
	ds_read_b128 v[64:67], v16 offset:1472
	v_add_u32_e32 v17, 0x8e80, v15
	s_waitcnt lgkmcnt(3)
	v_mfma_f32_16x16x32_bf16 v[48:51], v[56:59], v[120:123], v[48:51]
	v_mfma_f32_16x16x32_bf16 v[40:43], v[44:47], v[120:123], v[40:43]
	v_add_u32_e32 v46, 0x8e88, v15
	ds_read2_b32 v[44:45], v17 offset1:1
	ds_read2_b32 v[46:47], v46 offset1:1
	ds_read_b128 v[120:123], v16 offset:1536
	v_add_u32_e32 v17, 0x8ec0, v15
	s_waitcnt lgkmcnt(3)
	v_mfma_f32_16x16x32_bf16 v[48:51], v[60:63], v[64:67], v[48:51]
	v_mfma_f32_16x16x32_bf16 v[40:43], v[52:55], v[64:67], v[40:43]
	v_add_u32_e32 v54, 0x8ec8, v15
	ds_read2_b32 v[52:53], v17 offset1:1
	ds_read2_b32 v[54:55], v54 offset1:1
	ds_read_b128 v[64:67], v16 offset:1600
	v_add_u32_e32 v17, 0x8f00, v15
	s_waitcnt lgkmcnt(3)
	v_mfma_f32_16x16x32_bf16 v[48:51], v[44:47], v[120:123], v[48:51]
	v_mfma_f32_16x16x32_bf16 v[40:43], v[56:59], v[120:123], v[40:43]
	v_add_u32_e32 v58, 0x8f08, v15
	ds_read2_b32 v[56:57], v17 offset1:1
	ds_read2_b32 v[58:59], v58 offset1:1
	ds_read_b128 v[120:123], v16 offset:1664
	v_add_u32_e32 v17, 0x8f40, v15
	s_waitcnt lgkmcnt(3)
	v_mfma_f32_16x16x32_bf16 v[48:51], v[52:55], v[64:67], v[48:51]
	v_mfma_f32_16x16x32_bf16 v[40:43], v[60:63], v[64:67], v[40:43]
	v_add_u32_e32 v62, 0x8f48, v15
	ds_read2_b32 v[60:61], v17 offset1:1
	ds_read2_b32 v[62:63], v62 offset1:1
	ds_read_b128 v[64:67], v16 offset:1728
	v_add_u32_e32 v17, 0x8f80, v15
	s_waitcnt lgkmcnt(3)
	v_mfma_f32_16x16x32_bf16 v[48:51], v[56:59], v[120:123], v[48:51]
	v_mfma_f32_16x16x32_bf16 v[40:43], v[44:47], v[120:123], v[40:43]
	v_add_u32_e32 v46, 0x8f88, v15
	ds_read2_b32 v[44:45], v17 offset1:1
	ds_read2_b32 v[46:47], v46 offset1:1
	ds_read_b128 v[120:123], v16 offset:1792
	v_add_u32_e32 v17, 0x8fc0, v15
	s_waitcnt lgkmcnt(3)
	v_mfma_f32_16x16x32_bf16 v[48:51], v[60:63], v[64:67], v[48:51]
	v_mfma_f32_16x16x32_bf16 v[40:43], v[52:55], v[64:67], v[40:43]
	v_add_u32_e32 v54, 0x8fc8, v15
	ds_read2_b32 v[52:53], v17 offset1:1
	ds_read2_b32 v[54:55], v54 offset1:1
	ds_read_b128 v[64:67], v16 offset:1856
	s_waitcnt lgkmcnt(3)
	v_mfma_f32_16x16x32_bf16 v[48:51], v[44:47], v[120:123], v[48:51]
	v_add_u32_e32 v17, 0x9000, v15
	v_mfma_f32_16x16x32_bf16 v[40:43], v[56:59], v[120:123], v[40:43]
	ds_read2_b32 v[56:57], v17 offset1:1
	ds_read2_b32 v[58:59], v115 offset1:1
	ds_read_b128 v[120:123], v16 offset:1920
	v_add_u32_e32 v17, 0x9040, v15
	v_add_u32_e32 v115, 0x9088, v15
	s_waitcnt lgkmcnt(3)
	v_mfma_f32_16x16x32_bf16 v[48:51], v[52:55], v[64:67], v[48:51]
	v_mfma_f32_16x16x32_bf16 v[40:43], v[60:63], v[64:67], v[40:43]
	v_add_u32_e32 v62, 0x9048, v15
	ds_read2_b32 v[60:61], v17 offset1:1
	ds_read2_b32 v[62:63], v62 offset1:1
	v_add_u32_e32 v17, 0x9080, v15
	s_waitcnt lgkmcnt(2)
	v_mfma_f32_16x16x32_bf16 v[48:51], v[56:59], v[120:123], v[48:51]
	ds_read_b128 v[64:67], v16 offset:1984
	v_mfma_f32_16x16x32_bf16 v[40:43], v[44:47], v[120:123], v[40:43]
	ds_read2_b32 v[44:45], v17 offset1:1
	ds_read2_b32 v[46:47], v115 offset1:1
	ds_read_b128 v[120:123], v16 offset:2048
	s_cmp_eq_u32 s8, 0
	s_cselect_b32 s74, s72, s73
	v_mov_b32_e32 v16, s74
	v_add_u32_e32 v17, 0x90c0, v15
	s_waitcnt lgkmcnt(3)
	v_mfma_f32_16x16x32_bf16 v[48:51], v[60:63], v[64:67], v[48:51]
	s_and_b64 s[6:7], s[4:5], exec
	v_add_u32_e32 v15, 0x90c8, v15
	s_cselect_b32 s6, s45, 0x6880
	v_mfma_f32_16x16x32_bf16 v[40:43], v[52:55], v[64:67], v[40:43]
	ds_read2_b32 v[52:53], v17 offset1:1
	ds_read2_b32 v[54:55], v15 offset1:1
	s_add_i32 s12, s6, 0
	v_add_u32_e32 v17, s12, v108
	s_waitcnt lgkmcnt(2)
	v_mfma_f32_16x16x32_bf16 v[44:47], v[44:47], v[120:123], v[48:51]
	v_add_u32_e32 v15, s9, v107
	s_nop 1
	ds_read_b64 v[48:49], v17
	ds_read_b64 v[50:51], v15
	s_and_b64 vcc, exec, s[2:3]
	s_waitcnt lgkmcnt(2)
	v_mfma_f32_16x16x32_bf16 v[44:47], v[52:55], v[116:119], v[44:47]
	s_mov_b64 s[6:7], -1
	s_waitcnt lgkmcnt(1)
	v_lshlrev_b32_e32 v15, 16, v48
	s_waitcnt lgkmcnt(0)
	v_lshlrev_b32_e32 v17, 16, v50
	v_mfma_f32_16x16x32_bf16 v[40:43], v[56:59], v[120:123], v[40:43]
	v_mfma_f32_16x16x32_bf16 v[40:43], v[60:63], v[116:119], v[40:43]
	v_fma_f32 v17, v16, v17, v44
	v_and_b32_e32 v44, 0xffff0000, v50
	v_mul_f32_e32 v15, v17, v15
	v_and_b32_e32 v17, 0xffff0000, v48
	v_fma_f32 v44, v16, v44, v45
	v_lshlrev_b32_e32 v45, 16, v51
	v_mul_f32_e32 v17, v44, v17
	v_lshlrev_b32_e32 v44, 16, v49
	v_fma_f32 v45, v16, v45, v46
	v_and_b32_e32 v46, 0xffff0000, v51
	v_mul_f32_e32 v44, v45, v44
	v_and_b32_e32 v45, 0xffff0000, v49
	v_fmac_f32_e32 v47, v16, v46
	v_mul_f32_e32 v45, v47, v45
	s_cbranch_vccz .LBB0_1884
	v_cvt_pk_bf16_f32 v46, v15, v14
	global_store_short v[68:69], v46, off
	v_cvt_pk_bf16_f32 v46, v17, v14
	global_store_short v[68:69], v46, off offset:2048
	v_cvt_pk_bf16_f32 v46, v44, v14
	global_store_short v[70:71], v46, off
	v_cvt_pk_bf16_f32 v46, v45, v14
	global_store_short v[72:73], v46, off
	s_mov_b64 s[6:7], 0

.LBB0_1926:
	s_or_b64 exec, exec, s[0:1]
	s_load_dwordx4 s[4:7], s[92:93], 0x70
	s_load_dwordx2 s[76:77], s[92:93], 0xb0
	s_mov_b32 s19, s13
	s_lshl_b64 s[2:3], s[18:19], 2
	v_lshlrev_b32_e32 v15, 3, v22
	v_ashrrev_i32_e32 v16, 31, v22
	s_waitcnt lgkmcnt(0)
	s_lshl_b32 s78, s18, 2
	s_add_u32 s78, s76, s78
	s_addc_u32 s79, s77, 0
	s_load_dword s72, s[78:79], 0x2000
	s_load_dword s73, s[78:79], 0x3000
	s_add_u32 s0, s4, s2
	s_addc_u32 s1, s5, s3
	s_load_dword s60, s[0:1], 0x9000
	s_load_dword s61, s[0:1], 0xf000
	s_load_dword s62, s[0:1], 0xa000
	s_load_dword s63, s[0:1], 0x10000
	s_load_dword s64, s[0:1], 0xc000
	s_add_u32 s2, s6, s2
	s_addc_u32 s3, s7, s3
	s_load_dword s65, s[2:3], 0x3000
	s_load_dword s66, s[0:1], 0xd000
	s_load_dword s67, s[2:3], 0x4000
	v_bfe_i32 v23, v22, 28, 1
	s_waitcnt lgkmcnt(0)
	v_mov_b32_e32 v25, s60
	v_mov_b32_e32 v24, s61
	v_mov_b32_e32 v29, s62
	v_mov_b32_e32 v28, s63
	v_mov_b32_e32 v27, s64
	v_mov_b32_e32 v17, s65
	v_mov_b32_e32 v31, s66
	v_mov_b32_e32 v45, s67
	v_lshrrev_b32_e32 v26, 27, v16
	v_add_u32_sdwa v23, v15, v23 dst_sel:DWORD dst_unused:UNUSED_PAD src0_sel:DWORD src1_sel:BYTE_3
	v_add_u32_e32 v26, v22, v26
	v_and_b32_e32 v23, 0xffffff00, v23
	v_ashrrev_i32_e32 v52, 5, v26
	v_sub_u32_e32 v26, v15, v23
	v_lshlrev_b32_e32 v23, 9, v52
	v_lshlrev_b32_e32 v55, 1, v26
	v_add3_u32 v23, 0, v23, v55
	v_and_b32_e32 v34, 0xffff0000, v2
	v_lshlrev_b32_e32 v33, 16, v1
	v_lshlrev_b32_e32 v36, 16, v3
	v_and_b32_e32 v39, 0xffff0000, v5
	v_and_b32_e32 v38, 0xffff0000, v4
	v_lshlrev_b32_e32 v41, 16, v5
	v_lshlrev_b32_e32 v40, 16, v80
	v_mov_b32_e32 v32, v34
	v_lshlrev_b32_e32 v30, 16, v2
	v_and_b32_e32 v35, 0xffff0000, v3
	v_lshlrev_b32_e32 v37, 16, v4
	v_mov_b32_e32 v48, v36
	v_mov_b32_e32 v49, v34
	v_pk_mov_b32 v[50:51], v[40:41], v[38:39] op_sel:[1,0]
	v_and_b32_e32 v47, 0xffff0000, v7
	v_and_b32_e32 v46, 0xffff0000, v6
	v_lshlrev_b32_e32 v54, 16, v6
	v_mov_b32_e32 v42, v46
	v_lshlrev_b32_e32 v43, 16, v81
	v_cmp_gt_i32_e32 vcc, s55, v22
	v_mov_b32_e32 v56, v25
	v_pk_mul_f32 v[32:33], v[24:25], v[32:33]
	v_mov_b32_e32 v57, v24
	v_pk_mul_f32 v[58:59], v[24:25], v[40:41]
	v_mad_u64_u32 v[52:53], s[4:5], v52, s54, v[26:27]
	v_lshl_add_u32 v64, v52, 1, 0
	s_load_dword s68, s[0:1], 0xb000
	s_load_dword s69, s[0:1], 0xe000
	s_load_dword s70, s[0:1], 0x11000
	s_load_dword s71, s[2:3], 0x5000
	v_mov_b32_e32 v26, v24
	v_fma_f32 v33, v27, v30, v33
	v_pk_mul_f32 v[60:61], v[56:57], v[34:35]
	v_pk_mul_f32 v[48:49], v[26:27], v[48:49]
	v_pk_mul_f32 v[62:63], v[56:57], v[36:37]
	v_mov_b32_e32 v34, v38
	v_pk_mul_f32 v[56:57], v[56:57], v[38:39]
	v_pk_mul_f32 v[50:51], v[26:27], v[50:51]
	v_fma_f32 v26, v27, v39, v59
	v_add_f32_e32 v38, v32, v33
	v_fma_f32 v30, v25, v30, v49
	v_fma_f32 v36, v27, v36, v60
	v_fma_f32 v39, v27, v35, v62
	v_pk_mul_f32 v[32:33], v[24:25], v[34:35]
	v_fma_f32 v24, v25, v37, v51
	v_fma_f32 v25, v27, v41, v56
	v_add_f32_e32 v26, v58, v26
	v_add_f32_e32 v30, v48, v30
	v_add_f32_e32 v35, v61, v36
	v_add_f32_e32 v36, v63, v39
	v_fma_f32 v27, v27, v37, v33
	v_add_f32_e32 v24, v50, v24
	v_add_f32_e32 v25, v57, v25
	s_waitcnt lgkmcnt(0)
	v_mov_b32_e32 v53, s68
	v_mov_b32_e32 v55, s69
	v_mov_b32_e32 v52, s70
	v_mov_b32_e32 v65, s71
	v_add_f32_e32 v34, v17, v38
	v_add_f32_e32 v26, v17, v26
	v_add_f32_e32 v30, v17, v30
	v_add_f32_e32 v33, v17, v35
	v_add_f32_e32 v35, v17, v36
	v_add_f32_e32 v27, v32, v27
	v_add_f32_e32 v32, v17, v24
	v_add_f32_e32 v36, v17, v25
	v_cvt_pk_bf16_f32 v24, v34, v30
	v_cvt_pk_bf16_f32 v25, v33, v35
	v_add_f32_e32 v17, v17, v27
	v_cvt_pk_bf16_f32 v27, v36, v26
	v_cvt_pk_bf16_f32 v26, v17, v32
	ds_write_b128 v64, v[24:27] offset:128
	v_mov_b32_e32 v24, v29
	v_mov_b32_e32 v25, v28
	v_pk_mul_f32 v[26:27], v[24:25], v[46:47]
	v_lshlrev_b32_e32 v32, 16, v7
	v_fma_f32 v26, v31, v32, v26
	v_lshlrev_b32_e32 v33, 16, v8
	v_add_f32_e32 v26, v27, v26
	v_add_f32_e32 v39, v45, v26
	v_pk_mul_f32 v[26:27], v[24:25], v[32:33]
	v_mov_b32_e32 v30, v28
	v_mov_b32_e32 v34, v32
	v_mov_b32_e32 v35, v46
	v_fma_f32 v26, v31, v47, v26
	v_pk_mul_f32 v[34:35], v[30:31], v[34:35]
	v_add_f32_e32 v26, v27, v26
	v_fma_f32 v35, v29, v54, v35
	v_add_f32_e32 v32, v45, v26
	v_and_b32_e32 v26, 0xffff0000, v8
	v_add_f32_e32 v34, v34, v35
	v_mov_b32_e32 v46, v26
	v_add_f32_e32 v38, v45, v34
	v_pk_mul_f32 v[34:35], v[28:29], v[46:47]
	v_and_b32_e32 v27, 0xffff0000, v9
	v_fma_f32 v35, v31, v33, v35
	v_add_f32_e32 v34, v34, v35
	v_add_f32_e32 v40, v45, v34
	v_pk_mul_f32 v[24:25], v[24:25], v[26:27]
	v_lshlrev_b32_e32 v35, 16, v9
	v_lshlrev_b32_e32 v34, 16, v82
	v_pk_mov_b32 v[36:37], v[34:35], v[26:27] op_sel:[1,0]
	v_fma_f32 v24, v31, v35, v24
	v_pk_mul_f32 v[36:37], v[30:31], v[36:37]
	v_add_f32_e32 v24, v25, v24
	v_fma_f32 v26, v29, v33, v37
	v_add_f32_e32 v30, v45, v24
	v_pk_mul_f32 v[24:25], v[28:29], v[34:35]
	v_pk_mul_f32 v[42:43], v[28:29], v[42:43]
	v_add_f32_e32 v26, v36, v26
	v_fma_f32 v25, v31, v27, v25
	v_fma_f32 v17, v31, v54, v43
	v_add_f32_e32 v26, v45, v26
	v_add_f32_e32 v24, v24, v25
	v_add_f32_e32 v17, v42, v17
	v_add_f32_e32 v27, v45, v24
	v_cvt_pk_bf16_f32 v26, v40, v26
	v_add_f32_e32 v17, v45, v17
	v_cvt_pk_bf16_f32 v24, v17, v38
	v_cvt_pk_bf16_f32 v25, v39, v32
	v_cvt_pk_bf16_f32 v27, v30, v27
	ds_write_b128 v23, v[24:27] offset:25088
	v_and_b32_e32 v26, 0xffff0000, v10
	v_lshlrev_b32_e32 v25, 16, v83
	v_mov_b32_e32 v24, v26
	v_lshlrev_b32_e32 v17, 16, v10
	v_pk_mul_f32 v[24:25], v[52:53], v[24:25]
	v_and_b32_e32 v27, 0xffff0000, v11
	v_fma_f32 v25, v55, v17, v25
	v_add_f32_e32 v24, v24, v25
	v_add_f32_e32 v34, v65, v24
	v_mov_b32_e32 v24, v53
	v_mov_b32_e32 v25, v52
	v_pk_mul_f32 v[28:29], v[24:25], v[26:27]
	v_lshlrev_b32_e32 v30, 16, v11
	v_lshlrev_b32_e32 v31, 16, v12
	v_mov_b32_e32 v33, v26
	v_fma_f32 v26, v55, v30, v28
	v_add_f32_e32 v26, v29, v26
	v_pk_mul_f32 v[28:29], v[24:25], v[30:31]
	v_add_f32_e32 v35, v65, v26
	v_fma_f32 v26, v55, v27, v28
	v_add_f32_e32 v26, v29, v26
	v_and_b32_e32 v28, 0xffff0000, v12
	v_mov_b32_e32 v32, v30
	v_add_f32_e32 v30, v65, v26
	v_mov_b32_e32 v26, v28
	v_pk_mul_f32 v[26:27], v[52:53], v[26:27]
	v_mov_b32_e32 v54, v52
	v_fma_f32 v27, v55, v31, v27
	v_pk_mul_f32 v[32:33], v[54:55], v[32:33]
	v_and_b32_e32 v29, 0xffff0000, v13
	v_add_f32_e32 v26, v26, v27
	v_fma_f32 v17, v53, v17, v33
	v_add_f32_e32 v36, v65, v26
	v_pk_mul_f32 v[24:25], v[24:25], v[28:29]
	v_lshlrev_b32_e32 v27, 16, v13
	v_lshlrev_b32_e32 v26, 16, v84
	v_add_f32_e32 v17, v32, v17
	v_pk_mov_b32 v[32:33], v[26:27], v[28:29] op_sel:[1,0]
	v_fma_f32 v24, v55, v27, v24
	v_pk_mul_f32 v[32:33], v[54:55], v[32:33]
	v_add_f32_e32 v24, v25, v24
	v_fma_f32 v28, v53, v31, v33
	v_add_f32_e32 v31, v65, v24
	v_pk_mul_f32 v[24:25], v[52:53], v[26:27]
	v_add_f32_e32 v28, v32, v28
	v_fma_f32 v25, v55, v29, v25
	v_add_f32_e32 v24, v24, v25
	v_add_f32_e32 v27, v65, v24
	v_add_f32_e32 v17, v65, v17
	v_add_f32_e32 v28, v65, v28
	v_cvt_pk_bf16_f32 v24, v34, v17
	v_cvt_pk_bf16_f32 v25, v35, v30
	v_cvt_pk_bf16_f32 v26, v36, v28
	v_cvt_pk_bf16_f32 v27, v31, v27
	ds_write_b128 v23, v[24:27] offset:33280
	s_and_saveexec_b64 s[0:1], vcc
	s_cbranch_execz .LBB0_1928
	v_lshrrev_b32_e32 v16, 26, v16
	v_add_u32_e32 v16, v22, v16
	v_ashrrev_i32_e32 v17, 6, v16
	v_lshlrev_b32_e32 v16, 9, v17
	v_sub_u32_e32 v16, v15, v16
	v_mad_u64_u32 v[24:25], s[2:3], v17, s56, v[16:17]
	v_lshl_add_u32 v15, v24, 1, 0
	ds_write_b128 v15, v[18:21] offset:41600
	v_mul_lo_u32 v15, v17, s57
	v_lshlrev_b32_e32 v16, 1, v16
	v_add3_u32 v15, 0, v15, v16
	ds_write_b128 v15, v[18:21] offset:42894

.LBB0_1943:
	s_xor_b64 s[2:3], s[4:5], -1
	s_and_b64 s[6:7], s[4:5], exec
	s_cselect_b32 s9, 0, 0x3100
	s_lshl_b32 s6, s8, 10
	s_or_b32 s12, s6, s18
	s_lshl_b64 s[6:7], s[12:13], 2
	s_waitcnt lgkmcnt(0)
	s_add_u32 s6, s0, s6
	s_addc_u32 s7, s1, s7
	s_cmp_eq_u32 s8, 0
	s_cselect_b32 s74, s72, s73
	v_mov_b32_e32 v15, s74
	v_lshl_or_b32 v17, s8, 1, v23
	s_add_i32 s9, s9, 0
	v_mov_b32_e32 v28, 0
	v_add_u32_e32 v16, s9, v45
	v_mad_u32_u24 v17, v17, s56, v50
	s_mov_b32 s6, -2
	v_mov_b32_e32 v29, v28
	v_mov_b32_e32 v30, v28
	v_mov_b32_e32 v31, v28
	v_mov_b32_e32 v24, v28
	v_mov_b32_e32 v25, v28
	v_mov_b32_e32 v26, v28
	v_mov_b32_e32 v27, v28
.LBB0_1944:
	ds_read2_b32 v[52:53], v17 offset0:8 offset1:9
	ds_read2_b32 v[54:55], v17 offset0:10 offset1:11
	ds_read2_b32 v[56:57], v17 offset1:1
	ds_read2_b32 v[58:59], v17 offset0:2 offset1:3
	ds_read_b128 v[60:63], v16
	ds_read2_b32 v[64:65], v17 offset0:24 offset1:25
	ds_read_b128 v[68:71], v16 offset:64
	s_add_i32 s6, s6, 4
	s_cmp_gt_u32 s6, 5
	s_waitcnt lgkmcnt(2)
	v_mfma_f32_16x16x32_bf16 v[28:31], v[52:55], v[60:63], v[28:31]
	ds_read2_b32 v[66:67], v17 offset0:26 offset1:27
	ds_read2_b32 v[52:53], v17 offset0:16 offset1:17
	v_mfma_f32_16x16x32_bf16 v[24:27], v[56:59], v[60:63], v[24:27]
	ds_read2_b32 v[54:55], v17 offset0:18 offset1:19
	ds_read2_b32 v[56:57], v17 offset0:40 offset1:41
	ds_read2_b32 v[58:59], v17 offset0:42 offset1:43
	s_waitcnt lgkmcnt(4)
	v_mfma_f32_16x16x32_bf16 v[28:31], v[64:67], v[68:71], v[28:31]
	s_waitcnt lgkmcnt(2)
	v_mfma_f32_16x16x32_bf16 v[24:27], v[52:55], v[68:71], v[24:27]
	ds_read_b128 v[52:55], v16 offset:128
	ds_read2_b32 v[60:61], v17 offset0:34 offset1:35
	ds_read_b128 v[62:65], v16 offset:192
	v_add_u32_e32 v16, 0x100, v16
	s_waitcnt lgkmcnt(2)
	v_mfma_f32_16x16x32_bf16 v[28:31], v[56:59], v[52:55], v[28:31]
	ds_read2_b32 v[58:59], v17 offset0:32 offset1:33
	ds_read2_b32 v[56:57], v17 offset0:56 offset1:57
	s_waitcnt lgkmcnt(1)
	v_mfma_f32_16x16x32_bf16 v[24:27], v[58:61], v[52:55], v[24:27]
	ds_read2_b32 v[58:59], v17 offset0:58 offset1:59
	ds_read2_b32 v[54:55], v17 offset0:50 offset1:51
	ds_read2_b32 v[52:53], v17 offset0:48 offset1:49
	v_add_u32_e32 v17, 0x100, v17
	s_waitcnt lgkmcnt(2)
	v_mfma_f32_16x16x32_bf16 v[28:31], v[56:59], v[62:65], v[28:31]
	s_waitcnt lgkmcnt(0)
	v_mfma_f32_16x16x32_bf16 v[24:27], v[52:55], v[62:65], v[24:27]
	s_cbranch_scc0 .LBB0_1944
	s_and_b64 s[6:7], s[4:5], exec
	s_cselect_b32 s6, s59, 0x8200
	s_add_i32 s12, s6, 0
	v_add_u32_e32 v16, s9, v46
	ds_read_b64 v[52:53], v16
	v_add_u32_e32 v16, s12, v47
	ds_read_b64 v[54:55], v16
	s_mov_b64 s[6:7], -1
	s_and_b64 vcc, exec, s[2:3]
	s_waitcnt lgkmcnt(1)
	v_lshlrev_b32_e32 v16, 16, v52
	v_fma_f32 v16, v15, v16, v28
	s_waitcnt lgkmcnt(0)
	v_lshlrev_b32_e32 v17, 16, v54
	v_and_b32_e32 v28, 0xffff0000, v52
	v_mul_f32_e32 v16, v16, v17
	v_and_b32_e32 v17, 0xffff0000, v54
	v_fma_f32 v28, v15, v28, v29
	v_lshlrev_b32_e32 v29, 16, v53
	v_mul_f32_e32 v17, v28, v17
	v_lshlrev_b32_e32 v28, 16, v55
	v_fma_f32 v29, v15, v29, v30
	v_and_b32_e32 v30, 0xffff0000, v53
	v_mul_f32_e32 v28, v29, v28
	v_and_b32_e32 v29, 0xffff0000, v55
	v_fmac_f32_e32 v31, v15, v30
	v_mul_f32_e32 v29, v31, v29
	s_cbranch_vccz .LBB0_1947
	v_cvt_pk_bf16_f32 v30, v16, v14
	global_store_short v[32:33], v30, off
	v_cvt_pk_bf16_f32 v30, v17, v14
	global_store_short v[32:33], v30, off offset:2048
	v_cvt_pk_bf16_f32 v30, v28, v14
	global_store_short v[34:35], v30, off
	v_cvt_pk_bf16_f32 v30, v29, v14
	global_store_short v[36:37], v30, off
	s_mov_b64 s[6:7], 0
